# scan consumer: on even steps the next loads are issued before the lgkm wait (count skips them)
# baseline (speedup 1.0000x reference)
.Lscan_cons_chunk:
	s_nop 0
	v_cndmask_b32_e64 v2, v4, v5, s[42:43]
	v_add_lshl_u32 v2, v2, s80, 10
	v_mov_b32_e64 v3, v180
	s_add_i32 s28, s28, 0x10000
	v_lshl_add_u64 v[2:3], v[0:1], 0, v[2:3]
	v_add_u32_e64 v5, 64, v5
	v_subrev_u32_e64 v4, 64, v4
	ds_read_b128 v[88:91], v10 offset:2304
	ds_read_b128 v[96:99], v10 offset:2816
	ds_read_b128 v[92:95], v10 offset:2560
	s_waitcnt lgkmcnt(3)
	s_nop 0
	v_fma_mix_f32 v12, v6, v20, v180 op_sel_hi:[0,1,0]
	v_fma_mix_f32 v12, v7, v20, v12 op_sel:[0,1,0] op_sel_hi:[0,1,0]
	v_fma_mix_f32 v12, v8, v21, v12 op_sel_hi:[0,1,0]
	v_fma_mix_f32 v12, v9, v21, v12 op_sel:[0,1,0] op_sel_hi:[0,1,0]
	s_nop 1
	s_nop 0
	v_add_f32_dpp v12, v12, v12 row_ror:1 row_mask:0xf bank_mask:0xf bound_ctrl:1
	s_nop 1
	s_nop 0
	v_add_f32_dpp v12, v12, v12 row_ror:2 row_mask:0xf bank_mask:0xf bound_ctrl:1
	v_pk_fma_f32 v[48:49], v[28:29], v[66:67], v[6:7] op_sel_hi:[1,0,1]
	v_pk_fma_f32 v[50:51], v[30:31], v[66:67], v[8:9] op_sel_hi:[1,0,1]
	v_add_f32_dpp v12, v12, v12 row_ror:4 row_mask:0xf bank_mask:0xf bound_ctrl:1
	v_add_f32_dpp v130, v130, v130 row_ror:8 row_mask:0xf bank_mask:0xc
	v_add_f32_dpp v130, v122, v122 row_ror:8 row_mask:0xf bank_mask:0x3
	v_add_f32_dpp v131, v131, v131 row_ror:8 row_mask:0xf bank_mask:0xc
	v_add_f32_dpp v12, v12, v12 row_ror:8 row_mask:0xf bank_mask:0xf bound_ctrl:1
	v_pk_fma_f32 v[6:7], v[24:25], v[12:13], v[48:49] op_sel_hi:[1,0,1] neg_lo:[1,0,0] neg_hi:[1,0,0]
	v_pk_fma_f32 v[8:9], v[26:27], v[12:13], v[50:51] op_sel_hi:[1,0,1] neg_lo:[1,0,0] neg_hi:[1,0,0]
	ds_read_b128 v[110:113], v10 offset:3328
	ds_read_b128 v[106:109], v10 offset:3072
	ds_read_b128 v[118:121], v10 offset:3840
	ds_read_b128 v[114:117], v10 offset:3584
	ds_read_b128 v[70:73], v11 offset:256
	v_fma_mix_f32 v12, v6, v36, v180 op_sel_hi:[0,1,0]
	v_fma_mix_f32 v12, v7, v36, v12 op_sel:[0,1,0] op_sel_hi:[0,1,0]
	v_fma_mix_f32 v12, v8, v37, v12 op_sel_hi:[0,1,0]
	v_fma_mix_f32 v12, v9, v37, v12 op_sel:[0,1,0] op_sel_hi:[0,1,0]
	v_fma_mix_f32 v52, v6, v22, v180 op_sel_hi:[0,1,0]
	v_fma_mix_f32 v52, v7, v22, v52 op_sel:[0,1,0] op_sel_hi:[0,1,0]
	v_add_f32_dpp v12, v12, v12 row_ror:1 row_mask:0xf bank_mask:0xf bound_ctrl:1
	v_fma_mix_f32 v52, v8, v23, v52 op_sel_hi:[0,1,0]
	v_fma_mix_f32 v52, v9, v23, v52 op_sel:[0,1,0] op_sel_hi:[0,1,0]
	v_add_f32_dpp v12, v12, v12 row_ror:2 row_mask:0xf bank_mask:0xf bound_ctrl:1
	v_pk_fma_f32 v[48:49], v[44:45], v[66:67], v[6:7] op_sel:[0,1,0]
	v_pk_fma_f32 v[50:51], v[46:47], v[66:67], v[8:9] op_sel:[0,1,0]
	v_add_f32_dpp v12, v12, v12 row_ror:4 row_mask:0xf bank_mask:0xf bound_ctrl:1
	v_add_f32_dpp v131, v123, v123 row_ror:8 row_mask:0xf bank_mask:0x3
	v_add_f32_dpp v132, v132, v132 row_ror:8 row_mask:0xf bank_mask:0xc
	v_add_f32_dpp v132, v124, v124 row_ror:8 row_mask:0xf bank_mask:0x3
	v_add_f32_dpp v12, v12, v12 row_ror:8 row_mask:0xf bank_mask:0xf bound_ctrl:1
	v_pk_fma_f32 v[6:7], v[40:41], v[12:13], v[48:49] op_sel_hi:[1,0,1] neg_lo:[1,0,0] neg_hi:[1,0,0]
	v_pk_fma_f32 v[8:9], v[42:43], v[12:13], v[50:51] op_sel_hi:[1,0,1] neg_lo:[1,0,0] neg_hi:[1,0,0]
	ds_read_b128 v[20:23], v10 offset:4352
	ds_read_b128 v[28:31], v10 offset:4864
	ds_read_b128 v[24:27], v10 offset:4608
	s_waitcnt lgkmcnt(4)
	s_nop 0
	v_fma_mix_f32 v12, v6, v88, v180 op_sel_hi:[0,1,0]
	v_fma_mix_f32 v12, v7, v88, v12 op_sel:[0,1,0] op_sel_hi:[0,1,0]
	v_fma_mix_f32 v12, v8, v89, v12 op_sel_hi:[0,1,0]
	v_fma_mix_f32 v12, v9, v89, v12 op_sel:[0,1,0] op_sel_hi:[0,1,0]
	v_fma_mix_f32 v53, v6, v38, v180 op_sel_hi:[0,1,0]
	v_fma_mix_f32 v53, v7, v38, v53 op_sel:[0,1,0] op_sel_hi:[0,1,0]
	v_add_f32_dpp v12, v12, v12 row_ror:1 row_mask:0xf bank_mask:0xf bound_ctrl:1
	v_fma_mix_f32 v53, v8, v39, v53 op_sel_hi:[0,1,0]
	v_fma_mix_f32 v53, v9, v39, v53 op_sel:[0,1,0] op_sel_hi:[0,1,0]
	v_add_f32_dpp v12, v12, v12 row_ror:2 row_mask:0xf bank_mask:0xf bound_ctrl:1
	v_pk_fma_f32 v[48:49], v[96:97], v[68:69], v[6:7] op_sel_hi:[1,0,1]
	v_pk_fma_f32 v[50:51], v[98:99], v[68:69], v[8:9] op_sel_hi:[1,0,1]
	v_add_f32_dpp v12, v12, v12 row_ror:4 row_mask:0xf bank_mask:0xf bound_ctrl:1
	v_add_f32_dpp v133, v133, v133 row_ror:8 row_mask:0xf bank_mask:0xc
	v_add_f32_dpp v133, v125, v125 row_ror:8 row_mask:0xf bank_mask:0x3
	v_add_f32_dpp v134, v134, v134 row_ror:8 row_mask:0xf bank_mask:0xc
	v_add_f32_dpp v12, v12, v12 row_ror:8 row_mask:0xf bank_mask:0xf bound_ctrl:1
	v_pk_fma_f32 v[6:7], v[92:93], v[12:13], v[48:49] op_sel_hi:[1,0,1] neg_lo:[1,0,0] neg_hi:[1,0,0]
	v_pk_fma_f32 v[8:9], v[94:95], v[12:13], v[50:51] op_sel_hi:[1,0,1] neg_lo:[1,0,0] neg_hi:[1,0,0]
	ds_read_b128 v[36:39], v10 offset:5376
	ds_read_b128 v[44:47], v10 offset:5888
	ds_read_b128 v[40:43], v10 offset:5632
	v_fma_mix_f32 v12, v6, v110, v180 op_sel_hi:[0,1,0]
	v_fma_mix_f32 v12, v7, v110, v12 op_sel:[0,1,0] op_sel_hi:[0,1,0]
	v_fma_mix_f32 v12, v8, v111, v12 op_sel_hi:[0,1,0]
	v_fma_mix_f32 v12, v9, v111, v12 op_sel:[0,1,0] op_sel_hi:[0,1,0]
	v_fma_mix_f32 v54, v6, v90, v180 op_sel_hi:[0,1,0]
	v_fma_mix_f32 v54, v7, v90, v54 op_sel:[0,1,0] op_sel_hi:[0,1,0]
	v_add_f32_dpp v12, v12, v12 row_ror:1 row_mask:0xf bank_mask:0xf bound_ctrl:1
	v_fma_mix_f32 v54, v8, v91, v54 op_sel_hi:[0,1,0]
	v_fma_mix_f32 v54, v9, v91, v54 op_sel:[0,1,0] op_sel_hi:[0,1,0]
	v_add_f32_dpp v12, v12, v12 row_ror:2 row_mask:0xf bank_mask:0xf bound_ctrl:1
	v_pk_fma_f32 v[48:49], v[118:119], v[68:69], v[6:7] op_sel:[0,1,0]
	v_pk_fma_f32 v[50:51], v[120:121], v[68:69], v[8:9] op_sel:[0,1,0]
	v_add_f32_dpp v12, v12, v12 row_ror:4 row_mask:0xf bank_mask:0xf bound_ctrl:1
	v_add_f32_dpp v134, v126, v126 row_ror:8 row_mask:0xf bank_mask:0x3
	v_add_f32_dpp v135, v135, v135 row_ror:8 row_mask:0xf bank_mask:0xc
	v_add_f32_dpp v135, v127, v127 row_ror:8 row_mask:0xf bank_mask:0x3
	v_add_f32_dpp v12, v12, v12 row_ror:8 row_mask:0xf bank_mask:0xf bound_ctrl:1
	v_pk_fma_f32 v[6:7], v[114:115], v[12:13], v[48:49] op_sel_hi:[1,0,1] neg_lo:[1,0,0] neg_hi:[1,0,0]
	v_pk_fma_f32 v[8:9], v[116:117], v[12:13], v[50:51] op_sel_hi:[1,0,1] neg_lo:[1,0,0] neg_hi:[1,0,0]
	v_pk_mul_f32 v[6:7], v[6:7], v[106:107]
	v_pk_mul_f32 v[8:9], v[8:9], v[108:109]
	ds_read_b128 v[88:91], v10 offset:6400
	ds_read_b128 v[96:99], v10 offset:6912
	ds_read_b128 v[92:95], v10 offset:6656
	s_waitcnt lgkmcnt(3)
	s_nop 0
	v_fma_mix_f32 v12, v6, v20, v180 op_sel_hi:[0,1,0]
	v_fma_mix_f32 v12, v7, v20, v12 op_sel:[0,1,0] op_sel_hi:[0,1,0]
	v_fma_mix_f32 v12, v8, v21, v12 op_sel_hi:[0,1,0]
	v_fma_mix_f32 v12, v9, v21, v12 op_sel:[0,1,0] op_sel_hi:[0,1,0]
	v_fma_mix_f32 v55, v6, v112, v180 op_sel_hi:[0,1,0]
	v_fma_mix_f32 v55, v7, v112, v55 op_sel:[0,1,0] op_sel_hi:[0,1,0]
	v_add_f32_dpp v12, v12, v12 row_ror:1 row_mask:0xf bank_mask:0xf bound_ctrl:1
	v_fma_mix_f32 v55, v8, v113, v55 op_sel_hi:[0,1,0]
	v_fma_mix_f32 v55, v9, v113, v55 op_sel:[0,1,0] op_sel_hi:[0,1,0]
	v_add_f32_dpp v12, v12, v12 row_ror:2 row_mask:0xf bank_mask:0xf bound_ctrl:1
	v_pk_fma_f32 v[48:49], v[28:29], v[70:71], v[6:7] op_sel_hi:[1,0,1]
	v_pk_fma_f32 v[50:51], v[30:31], v[70:71], v[8:9] op_sel_hi:[1,0,1]
	v_add_f32_dpp v12, v12, v12 row_ror:4 row_mask:0xf bank_mask:0xf bound_ctrl:1
	v_add_f32_dpp v136, v136, v136 row_ror:8 row_mask:0xf bank_mask:0xc
	v_add_f32_dpp v136, v128, v128 row_ror:8 row_mask:0xf bank_mask:0x3
	v_add_f32_dpp v12, v12, v12 row_ror:8 row_mask:0xf bank_mask:0xf bound_ctrl:1
	v_pk_fma_f32 v[6:7], v[24:25], v[12:13], v[48:49] op_sel_hi:[1,0,1] neg_lo:[1,0,0] neg_hi:[1,0,0]
	v_pk_fma_f32 v[8:9], v[26:27], v[12:13], v[50:51] op_sel_hi:[1,0,1] neg_lo:[1,0,0] neg_hi:[1,0,0]
	ds_read_b128 v[110:113], v10 offset:7424
	ds_read_b128 v[106:109], v10 offset:7168
	ds_read_b128 v[118:121], v10 offset:7936
	ds_read_b128 v[114:117], v10 offset:7680
	ds_read_b128 v[66:69], v11 offset:512
	v_fma_mix_f32 v12, v6, v36, v180 op_sel_hi:[0,1,0]
	v_fma_mix_f32 v12, v7, v36, v12 op_sel:[0,1,0] op_sel_hi:[0,1,0]
	v_fma_mix_f32 v12, v8, v37, v12 op_sel_hi:[0,1,0]
	v_fma_mix_f32 v12, v9, v37, v12 op_sel:[0,1,0] op_sel_hi:[0,1,0]
	v_fma_mix_f32 v56, v6, v22, v180 op_sel_hi:[0,1,0]
	v_fma_mix_f32 v56, v7, v22, v56 op_sel:[0,1,0] op_sel_hi:[0,1,0]
	v_add_f32_dpp v12, v12, v12 row_ror:1 row_mask:0xf bank_mask:0xf bound_ctrl:1
	v_fma_mix_f32 v56, v8, v23, v56 op_sel_hi:[0,1,0]
	v_fma_mix_f32 v56, v9, v23, v56 op_sel:[0,1,0] op_sel_hi:[0,1,0]
	v_add_f32_dpp v12, v12, v12 row_ror:2 row_mask:0xf bank_mask:0xf bound_ctrl:1
	v_pk_fma_f32 v[48:49], v[44:45], v[70:71], v[6:7] op_sel:[0,1,0]
	v_pk_fma_f32 v[50:51], v[46:47], v[70:71], v[8:9] op_sel:[0,1,0]
	v_add_f32_dpp v12, v12, v12 row_ror:4 row_mask:0xf bank_mask:0xf bound_ctrl:1
	v_add_f32_dpp v137, v137, v137 row_ror:8 row_mask:0xf bank_mask:0xc
	v_add_f32_dpp v137, v129, v129 row_ror:8 row_mask:0xf bank_mask:0x3
	v_add_f32_dpp v12, v12, v12 row_ror:8 row_mask:0xf bank_mask:0xf bound_ctrl:1
	v_pk_fma_f32 v[6:7], v[40:41], v[12:13], v[48:49] op_sel_hi:[1,0,1] neg_lo:[1,0,0] neg_hi:[1,0,0]
	v_pk_fma_f32 v[8:9], v[42:43], v[12:13], v[50:51] op_sel_hi:[1,0,1] neg_lo:[1,0,0] neg_hi:[1,0,0]
	ds_read_b128 v[20:23], v10 offset:8448
	ds_read_b128 v[28:31], v10 offset:8960
	ds_read_b128 v[24:27], v10 offset:8704
	s_waitcnt lgkmcnt(4)
	s_nop 0
	v_fma_mix_f32 v12, v6, v88, v180 op_sel_hi:[0,1,0]
	v_fma_mix_f32 v12, v7, v88, v12 op_sel:[0,1,0] op_sel_hi:[0,1,0]
	v_fma_mix_f32 v12, v8, v89, v12 op_sel_hi:[0,1,0]
	v_fma_mix_f32 v12, v9, v89, v12 op_sel:[0,1,0] op_sel_hi:[0,1,0]
	v_fma_mix_f32 v57, v6, v38, v180 op_sel_hi:[0,1,0]
	v_fma_mix_f32 v57, v7, v38, v57 op_sel:[0,1,0] op_sel_hi:[0,1,0]
	v_add_f32_dpp v12, v12, v12 row_ror:1 row_mask:0xf bank_mask:0xf bound_ctrl:1
	v_fma_mix_f32 v57, v8, v39, v57 op_sel_hi:[0,1,0]
	v_fma_mix_f32 v57, v9, v39, v57 op_sel:[0,1,0] op_sel_hi:[0,1,0]
	v_add_f32_dpp v12, v12, v12 row_ror:2 row_mask:0xf bank_mask:0xf bound_ctrl:1
	v_pk_fma_f32 v[48:49], v[96:97], v[72:73], v[6:7] op_sel_hi:[1,0,1]
	v_pk_fma_f32 v[50:51], v[98:99], v[72:73], v[8:9] op_sel_hi:[1,0,1]
	v_add_f32_dpp v12, v12, v12 row_ror:4 row_mask:0xf bank_mask:0xf bound_ctrl:1
	v_add_f32_dpp v134, v134, v134 row_ror:4 row_mask:0xf bank_mask:0xa
	v_add_f32_dpp v134, v130, v130 row_ror:12 row_mask:0xf bank_mask:0x5
	v_add_f32_dpp v135, v135, v135 row_ror:4 row_mask:0xf bank_mask:0xa
	v_add_f32_dpp v12, v12, v12 row_ror:8 row_mask:0xf bank_mask:0xf bound_ctrl:1
	v_pk_fma_f32 v[6:7], v[92:93], v[12:13], v[48:49] op_sel_hi:[1,0,1] neg_lo:[1,0,0] neg_hi:[1,0,0]
	v_pk_fma_f32 v[8:9], v[94:95], v[12:13], v[50:51] op_sel_hi:[1,0,1] neg_lo:[1,0,0] neg_hi:[1,0,0]
	ds_read_b128 v[36:39], v10 offset:9472
	ds_read_b128 v[44:47], v10 offset:9984
	ds_read_b128 v[40:43], v10 offset:9728
	v_fma_mix_f32 v12, v6, v110, v180 op_sel_hi:[0,1,0]
	v_fma_mix_f32 v12, v7, v110, v12 op_sel:[0,1,0] op_sel_hi:[0,1,0]
	v_fma_mix_f32 v12, v8, v111, v12 op_sel_hi:[0,1,0]
	v_fma_mix_f32 v12, v9, v111, v12 op_sel:[0,1,0] op_sel_hi:[0,1,0]
	v_fma_mix_f32 v81, v6, v90, v180 op_sel_hi:[0,1,0]
	v_fma_mix_f32 v81, v7, v90, v81 op_sel:[0,1,0] op_sel_hi:[0,1,0]
	v_add_f32_dpp v12, v12, v12 row_ror:1 row_mask:0xf bank_mask:0xf bound_ctrl:1
	v_fma_mix_f32 v81, v8, v91, v81 op_sel_hi:[0,1,0]
	v_fma_mix_f32 v81, v9, v91, v81 op_sel:[0,1,0] op_sel_hi:[0,1,0]
	v_add_f32_dpp v12, v12, v12 row_ror:2 row_mask:0xf bank_mask:0xf bound_ctrl:1
	v_pk_fma_f32 v[48:49], v[118:119], v[72:73], v[6:7] op_sel:[0,1,0]
	v_pk_fma_f32 v[50:51], v[120:121], v[72:73], v[8:9] op_sel:[0,1,0]
	v_add_f32_dpp v12, v12, v12 row_ror:4 row_mask:0xf bank_mask:0xf bound_ctrl:1
	v_add_f32_dpp v135, v131, v131 row_ror:12 row_mask:0xf bank_mask:0x5
	v_add_f32_dpp v136, v136, v136 row_ror:4 row_mask:0xf bank_mask:0xa
	v_add_f32_dpp v136, v132, v132 row_ror:12 row_mask:0xf bank_mask:0x5
	v_add_f32_dpp v12, v12, v12 row_ror:8 row_mask:0xf bank_mask:0xf bound_ctrl:1
	v_pk_fma_f32 v[6:7], v[114:115], v[12:13], v[48:49] op_sel_hi:[1,0,1] neg_lo:[1,0,0] neg_hi:[1,0,0]
	v_pk_fma_f32 v[8:9], v[116:117], v[12:13], v[50:51] op_sel_hi:[1,0,1] neg_lo:[1,0,0] neg_hi:[1,0,0]
	v_pk_mul_f32 v[6:7], v[6:7], v[106:107]
	v_pk_mul_f32 v[8:9], v[8:9], v[108:109]
	ds_read_b128 v[88:91], v10 offset:10496
	ds_read_b128 v[96:99], v10 offset:11008
	ds_read_b128 v[92:95], v10 offset:10752
	s_waitcnt lgkmcnt(3)
	s_nop 0
	v_fma_mix_f32 v12, v6, v20, v180 op_sel_hi:[0,1,0]
	v_fma_mix_f32 v12, v7, v20, v12 op_sel:[0,1,0] op_sel_hi:[0,1,0]
	v_fma_mix_f32 v12, v8, v21, v12 op_sel_hi:[0,1,0]
	v_fma_mix_f32 v12, v9, v21, v12 op_sel:[0,1,0] op_sel_hi:[0,1,0]
	v_fma_mix_f32 v82, v6, v112, v180 op_sel_hi:[0,1,0]
	v_fma_mix_f32 v82, v7, v112, v82 op_sel:[0,1,0] op_sel_hi:[0,1,0]
	v_add_f32_dpp v12, v12, v12 row_ror:1 row_mask:0xf bank_mask:0xf bound_ctrl:1
	v_fma_mix_f32 v82, v8, v113, v82 op_sel_hi:[0,1,0]
	v_fma_mix_f32 v82, v9, v113, v82 op_sel:[0,1,0] op_sel_hi:[0,1,0]
	v_add_f32_dpp v12, v12, v12 row_ror:2 row_mask:0xf bank_mask:0xf bound_ctrl:1
	v_pk_fma_f32 v[48:49], v[28:29], v[66:67], v[6:7] op_sel_hi:[1,0,1]
	v_pk_fma_f32 v[50:51], v[30:31], v[66:67], v[8:9] op_sel_hi:[1,0,1]
	v_add_f32_dpp v12, v12, v12 row_ror:4 row_mask:0xf bank_mask:0xf bound_ctrl:1
	v_add_f32_dpp v137, v137, v137 row_ror:4 row_mask:0xf bank_mask:0xa
	v_add_f32_dpp v137, v133, v133 row_ror:12 row_mask:0xf bank_mask:0x5
	v_add_f32_dpp v12, v12, v12 row_ror:8 row_mask:0xf bank_mask:0xf bound_ctrl:1
	v_pk_fma_f32 v[6:7], v[24:25], v[12:13], v[48:49] op_sel_hi:[1,0,1] neg_lo:[1,0,0] neg_hi:[1,0,0]
	v_pk_fma_f32 v[8:9], v[26:27], v[12:13], v[50:51] op_sel_hi:[1,0,1] neg_lo:[1,0,0] neg_hi:[1,0,0]
	ds_read_b128 v[110:113], v10 offset:11520
	ds_read_b128 v[106:109], v10 offset:11264
	ds_read_b128 v[118:121], v10 offset:12032
	ds_read_b128 v[114:117], v10 offset:11776
	ds_read_b128 v[70:73], v11 offset:768
	v_fma_mix_f32 v12, v6, v36, v180 op_sel_hi:[0,1,0]
	v_fma_mix_f32 v12, v7, v36, v12 op_sel:[0,1,0] op_sel_hi:[0,1,0]
	v_fma_mix_f32 v12, v8, v37, v12 op_sel_hi:[0,1,0]
	v_fma_mix_f32 v12, v9, v37, v12 op_sel:[0,1,0] op_sel_hi:[0,1,0]
	v_fma_mix_f32 v83, v6, v22, v180 op_sel_hi:[0,1,0]
	v_fma_mix_f32 v83, v7, v22, v83 op_sel:[0,1,0] op_sel_hi:[0,1,0]
	v_add_f32_dpp v12, v12, v12 row_ror:1 row_mask:0xf bank_mask:0xf bound_ctrl:1
	v_fma_mix_f32 v83, v8, v23, v83 op_sel_hi:[0,1,0]
	v_fma_mix_f32 v83, v9, v23, v83 op_sel:[0,1,0] op_sel_hi:[0,1,0]
	v_add_f32_dpp v12, v12, v12 row_ror:2 row_mask:0xf bank_mask:0xf bound_ctrl:1
	v_pk_fma_f32 v[48:49], v[44:45], v[66:67], v[6:7] op_sel:[0,1,0]
	v_pk_fma_f32 v[50:51], v[46:47], v[66:67], v[8:9] op_sel:[0,1,0]
	v_add_f32_dpp v12, v12, v12 row_ror:4 row_mask:0xf bank_mask:0xf bound_ctrl:1
	v_cndmask_b32_e64 v62, v136, v134, s[38:39]
	v_cndmask_b32_e64 v63, v134, v136, s[38:39]
	v_add_f32_dpp v12, v12, v12 row_ror:8 row_mask:0xf bank_mask:0xf bound_ctrl:1
	v_pk_fma_f32 v[6:7], v[40:41], v[12:13], v[48:49] op_sel_hi:[1,0,1] neg_lo:[1,0,0] neg_hi:[1,0,0]
	v_pk_fma_f32 v[8:9], v[42:43], v[12:13], v[50:51] op_sel_hi:[1,0,1] neg_lo:[1,0,0] neg_hi:[1,0,0]
	ds_read_b128 v[20:23], v10 offset:12544
	ds_read_b128 v[28:31], v10 offset:13056
	ds_read_b128 v[24:27], v10 offset:12800
	s_waitcnt lgkmcnt(4)
	s_nop 0
	v_fma_mix_f32 v12, v6, v88, v180 op_sel_hi:[0,1,0]
	v_fma_mix_f32 v12, v7, v88, v12 op_sel:[0,1,0] op_sel_hi:[0,1,0]
	v_fma_mix_f32 v12, v8, v89, v12 op_sel_hi:[0,1,0]
	v_fma_mix_f32 v12, v9, v89, v12 op_sel:[0,1,0] op_sel_hi:[0,1,0]
	v_fma_mix_f32 v100, v6, v38, v180 op_sel_hi:[0,1,0]
	v_fma_mix_f32 v100, v7, v38, v100 op_sel:[0,1,0] op_sel_hi:[0,1,0]
	v_add_f32_dpp v12, v12, v12 row_ror:1 row_mask:0xf bank_mask:0xf bound_ctrl:1
	v_fma_mix_f32 v100, v8, v39, v100 op_sel_hi:[0,1,0]
	v_fma_mix_f32 v100, v9, v39, v100 op_sel:[0,1,0] op_sel_hi:[0,1,0]
	v_add_f32_dpp v12, v12, v12 row_ror:2 row_mask:0xf bank_mask:0xf bound_ctrl:1
	v_pk_fma_f32 v[48:49], v[96:97], v[68:69], v[6:7] op_sel_hi:[1,0,1]
	v_pk_fma_f32 v[50:51], v[98:99], v[68:69], v[8:9] op_sel_hi:[1,0,1]
	v_add_f32_dpp v12, v12, v12 row_ror:4 row_mask:0xf bank_mask:0xf bound_ctrl:1
	v_cndmask_b32_e64 v64, v137, v135, s[38:39]
	v_cndmask_b32_e64 v65, v135, v137, s[38:39]
	v_add_f32_dpp v12, v12, v12 row_ror:8 row_mask:0xf bank_mask:0xf bound_ctrl:1
	v_pk_fma_f32 v[6:7], v[92:93], v[12:13], v[48:49] op_sel_hi:[1,0,1] neg_lo:[1,0,0] neg_hi:[1,0,0]
	v_pk_fma_f32 v[8:9], v[94:95], v[12:13], v[50:51] op_sel_hi:[1,0,1] neg_lo:[1,0,0] neg_hi:[1,0,0]
	ds_read_b128 v[36:39], v10 offset:13568
	ds_read_b128 v[44:47], v10 offset:14080
	ds_read_b128 v[40:43], v10 offset:13824
	v_fma_mix_f32 v12, v6, v110, v180 op_sel_hi:[0,1,0]
	v_fma_mix_f32 v12, v7, v110, v12 op_sel:[0,1,0] op_sel_hi:[0,1,0]
	v_fma_mix_f32 v12, v8, v111, v12 op_sel_hi:[0,1,0]
	v_fma_mix_f32 v12, v9, v111, v12 op_sel:[0,1,0] op_sel_hi:[0,1,0]
	v_fma_mix_f32 v101, v6, v90, v180 op_sel_hi:[0,1,0]
	v_fma_mix_f32 v101, v7, v90, v101 op_sel:[0,1,0] op_sel_hi:[0,1,0]
	v_add_f32_dpp v12, v12, v12 row_ror:1 row_mask:0xf bank_mask:0xf bound_ctrl:1
	v_fma_mix_f32 v101, v8, v91, v101 op_sel_hi:[0,1,0]
	v_fma_mix_f32 v101, v9, v91, v101 op_sel:[0,1,0] op_sel_hi:[0,1,0]
	v_add_f32_dpp v12, v12, v12 row_ror:2 row_mask:0xf bank_mask:0xf bound_ctrl:1
	v_pk_fma_f32 v[48:49], v[118:119], v[68:69], v[6:7] op_sel:[0,1,0]
	v_pk_fma_f32 v[50:51], v[120:121], v[68:69], v[8:9] op_sel:[0,1,0]
	v_add_f32_dpp v12, v12, v12 row_ror:4 row_mask:0xf bank_mask:0xf bound_ctrl:1
	v_add_f32_dpp v62, v63, v62 quad_perm:[2,3,0,1] row_mask:0xf bank_mask:0xf bound_ctrl:1
	v_add_f32_dpp v63, v65, v64 quad_perm:[2,3,0,1] row_mask:0xf bank_mask:0xf bound_ctrl:1
	v_add_f32_dpp v12, v12, v12 row_ror:8 row_mask:0xf bank_mask:0xf bound_ctrl:1
	v_pk_fma_f32 v[6:7], v[114:115], v[12:13], v[48:49] op_sel_hi:[1,0,1] neg_lo:[1,0,0] neg_hi:[1,0,0]
	v_pk_fma_f32 v[8:9], v[116:117], v[12:13], v[50:51] op_sel_hi:[1,0,1] neg_lo:[1,0,0] neg_hi:[1,0,0]
	v_pk_mul_f32 v[6:7], v[6:7], v[106:107]
	v_pk_mul_f32 v[8:9], v[8:9], v[108:109]
	ds_read_b128 v[88:91], v10 offset:14592
	ds_read_b128 v[96:99], v10 offset:15104
	ds_read_b128 v[92:95], v10 offset:14848
	s_waitcnt lgkmcnt(3)
	s_nop 0
	v_fma_mix_f32 v12, v6, v20, v180 op_sel_hi:[0,1,0]
	v_fma_mix_f32 v12, v7, v20, v12 op_sel:[0,1,0] op_sel_hi:[0,1,0]
	v_fma_mix_f32 v12, v8, v21, v12 op_sel_hi:[0,1,0]
	v_fma_mix_f32 v12, v9, v21, v12 op_sel:[0,1,0] op_sel_hi:[0,1,0]
	v_fma_mix_f32 v102, v6, v112, v180 op_sel_hi:[0,1,0]
	v_fma_mix_f32 v102, v7, v112, v102 op_sel:[0,1,0] op_sel_hi:[0,1,0]
	v_add_f32_dpp v12, v12, v12 row_ror:1 row_mask:0xf bank_mask:0xf bound_ctrl:1
	v_fma_mix_f32 v102, v8, v113, v102 op_sel_hi:[0,1,0]
	v_fma_mix_f32 v102, v9, v113, v102 op_sel:[0,1,0] op_sel_hi:[0,1,0]
	v_add_f32_dpp v12, v12, v12 row_ror:2 row_mask:0xf bank_mask:0xf bound_ctrl:1
	v_pk_fma_f32 v[48:49], v[28:29], v[70:71], v[6:7] op_sel_hi:[1,0,1]
	v_pk_fma_f32 v[50:51], v[30:31], v[70:71], v[8:9] op_sel_hi:[1,0,1]
	v_add_f32_dpp v12, v12, v12 row_ror:4 row_mask:0xf bank_mask:0xf bound_ctrl:1
	v_cndmask_b32_e64 v65, v63, v62, s[40:41]
	v_cndmask_b32_e64 v62, v62, v63, s[40:41]
	v_add_f32_dpp v12, v12, v12 row_ror:8 row_mask:0xf bank_mask:0xf bound_ctrl:1
	v_pk_fma_f32 v[6:7], v[24:25], v[12:13], v[48:49] op_sel_hi:[1,0,1] neg_lo:[1,0,0] neg_hi:[1,0,0]
	v_pk_fma_f32 v[8:9], v[26:27], v[12:13], v[50:51] op_sel_hi:[1,0,1] neg_lo:[1,0,0] neg_hi:[1,0,0]
	ds_read_b128 v[110:113], v10 offset:15616
	ds_read_b128 v[106:109], v10 offset:15360
	ds_read_b128 v[118:121], v10 offset:16128
	ds_read_b128 v[114:117], v10 offset:15872
	ds_read_b128 v[66:69], v11 offset:1024
	v_fma_mix_f32 v12, v6, v36, v180 op_sel_hi:[0,1,0]
	v_fma_mix_f32 v12, v7, v36, v12 op_sel:[0,1,0] op_sel_hi:[0,1,0]
	v_fma_mix_f32 v12, v8, v37, v12 op_sel_hi:[0,1,0]
	v_fma_mix_f32 v12, v9, v37, v12 op_sel:[0,1,0] op_sel_hi:[0,1,0]
	v_fma_mix_f32 v103, v6, v22, v180 op_sel_hi:[0,1,0]
	v_fma_mix_f32 v103, v7, v22, v103 op_sel:[0,1,0] op_sel_hi:[0,1,0]
	v_add_f32_dpp v12, v12, v12 row_ror:1 row_mask:0xf bank_mask:0xf bound_ctrl:1
	v_fma_mix_f32 v103, v8, v23, v103 op_sel_hi:[0,1,0]
	v_fma_mix_f32 v103, v9, v23, v103 op_sel:[0,1,0] op_sel_hi:[0,1,0]
	v_add_f32_dpp v12, v12, v12 row_ror:2 row_mask:0xf bank_mask:0xf bound_ctrl:1
	v_pk_fma_f32 v[48:49], v[44:45], v[70:71], v[6:7] op_sel:[0,1,0]
	v_pk_fma_f32 v[50:51], v[46:47], v[70:71], v[8:9] op_sel:[0,1,0]
	v_add_f32_dpp v12, v12, v12 row_ror:4 row_mask:0xf bank_mask:0xf bound_ctrl:1
	v_add_f32_dpp v62, v62, v65 quad_perm:[1,0,3,2] row_mask:0xf bank_mask:0xf bound_ctrl:1
	v_cvt_pk_bf16_f32 v62, v62, v62
	v_add_f32_dpp v12, v12, v12 row_ror:8 row_mask:0xf bank_mask:0xf bound_ctrl:1
	v_pk_fma_f32 v[6:7], v[40:41], v[12:13], v[48:49] op_sel_hi:[1,0,1] neg_lo:[1,0,0] neg_hi:[1,0,0]
	v_pk_fma_f32 v[8:9], v[42:43], v[12:13], v[50:51] op_sel_hi:[1,0,1] neg_lo:[1,0,0] neg_hi:[1,0,0]
	ds_read_b128 v[20:23], v10 offset:16640
	ds_read_b128 v[28:31], v10 offset:17152
	ds_read_b128 v[24:27], v10 offset:16896
	s_waitcnt lgkmcnt(4)
	s_nop 0
	v_fma_mix_f32 v12, v6, v88, v180 op_sel_hi:[0,1,0]
	v_fma_mix_f32 v12, v7, v88, v12 op_sel:[0,1,0] op_sel_hi:[0,1,0]
	v_fma_mix_f32 v12, v8, v89, v12 op_sel_hi:[0,1,0]
	v_fma_mix_f32 v12, v9, v89, v12 op_sel:[0,1,0] op_sel_hi:[0,1,0]
	v_fma_mix_f32 v104, v6, v38, v180 op_sel_hi:[0,1,0]
	v_fma_mix_f32 v104, v7, v38, v104 op_sel:[0,1,0] op_sel_hi:[0,1,0]
	v_add_f32_dpp v12, v12, v12 row_ror:1 row_mask:0xf bank_mask:0xf bound_ctrl:1
	v_fma_mix_f32 v104, v8, v39, v104 op_sel_hi:[0,1,0]
	v_fma_mix_f32 v104, v9, v39, v104 op_sel:[0,1,0] op_sel_hi:[0,1,0]
	v_add_f32_dpp v12, v12, v12 row_ror:2 row_mask:0xf bank_mask:0xf bound_ctrl:1
	v_pk_fma_f32 v[48:49], v[96:97], v[72:73], v[6:7] op_sel_hi:[1,0,1]
	v_pk_fma_f32 v[50:51], v[98:99], v[72:73], v[8:9] op_sel_hi:[1,0,1]
	v_add_f32_dpp v12, v12, v12 row_ror:4 row_mask:0xf bank_mask:0xf bound_ctrl:1
	s_mov_b64 exec, s[100:101]
	s_nop 0
	global_store_short v[170:171], v62, off
	s_mov_b64 exec, -1
	s_nop 0
	v_add_f32_dpp v12, v12, v12 row_ror:8 row_mask:0xf bank_mask:0xf bound_ctrl:1
	v_pk_fma_f32 v[6:7], v[92:93], v[12:13], v[48:49] op_sel_hi:[1,0,1] neg_lo:[1,0,0] neg_hi:[1,0,0]
	v_pk_fma_f32 v[8:9], v[94:95], v[12:13], v[50:51] op_sel_hi:[1,0,1] neg_lo:[1,0,0] neg_hi:[1,0,0]
	ds_read_b128 v[36:39], v10 offset:17664
	ds_read_b128 v[44:47], v10 offset:18176
	ds_read_b128 v[40:43], v10 offset:17920
	v_fma_mix_f32 v12, v6, v110, v180 op_sel_hi:[0,1,0]
	v_fma_mix_f32 v12, v7, v110, v12 op_sel:[0,1,0] op_sel_hi:[0,1,0]
	v_fma_mix_f32 v12, v8, v111, v12 op_sel_hi:[0,1,0]
	v_fma_mix_f32 v12, v9, v111, v12 op_sel:[0,1,0] op_sel_hi:[0,1,0]
	v_fma_mix_f32 v105, v6, v90, v180 op_sel_hi:[0,1,0]
	v_fma_mix_f32 v105, v7, v90, v105 op_sel:[0,1,0] op_sel_hi:[0,1,0]
	v_add_f32_dpp v12, v12, v12 row_ror:1 row_mask:0xf bank_mask:0xf bound_ctrl:1
	v_fma_mix_f32 v105, v8, v91, v105 op_sel_hi:[0,1,0]
	v_fma_mix_f32 v105, v9, v91, v105 op_sel:[0,1,0] op_sel_hi:[0,1,0]
	v_add_f32_dpp v12, v12, v12 row_ror:2 row_mask:0xf bank_mask:0xf bound_ctrl:1
	v_pk_fma_f32 v[48:49], v[118:119], v[72:73], v[6:7] op_sel:[0,1,0]
	v_pk_fma_f32 v[50:51], v[120:121], v[72:73], v[8:9] op_sel:[0,1,0]
	v_add_f32_dpp v12, v12, v12 row_ror:4 row_mask:0xf bank_mask:0xf bound_ctrl:1
	s_nop 1
	s_nop 0
	v_add_f32_dpp v12, v12, v12 row_ror:8 row_mask:0xf bank_mask:0xf bound_ctrl:1
	v_pk_fma_f32 v[6:7], v[114:115], v[12:13], v[48:49] op_sel_hi:[1,0,1] neg_lo:[1,0,0] neg_hi:[1,0,0]
	v_pk_fma_f32 v[8:9], v[116:117], v[12:13], v[50:51] op_sel_hi:[1,0,1] neg_lo:[1,0,0] neg_hi:[1,0,0]
	v_pk_mul_f32 v[6:7], v[6:7], v[106:107]
	v_pk_mul_f32 v[8:9], v[8:9], v[108:109]
	ds_read_b128 v[88:91], v10 offset:18688
	ds_read_b128 v[96:99], v10 offset:19200
	ds_read_b128 v[92:95], v10 offset:18944
	s_waitcnt lgkmcnt(3)
	s_nop 0
	v_fma_mix_f32 v12, v6, v20, v180 op_sel_hi:[0,1,0]
	v_fma_mix_f32 v12, v7, v20, v12 op_sel:[0,1,0] op_sel_hi:[0,1,0]
	v_fma_mix_f32 v12, v8, v21, v12 op_sel_hi:[0,1,0]
	v_fma_mix_f32 v12, v9, v21, v12 op_sel:[0,1,0] op_sel_hi:[0,1,0]
	v_fma_mix_f32 v61, v6, v112, v180 op_sel_hi:[0,1,0]
	v_fma_mix_f32 v61, v7, v112, v61 op_sel:[0,1,0] op_sel_hi:[0,1,0]
	v_add_f32_dpp v12, v12, v12 row_ror:1 row_mask:0xf bank_mask:0xf bound_ctrl:1
	v_fma_mix_f32 v61, v8, v113, v61 op_sel_hi:[0,1,0]
	v_fma_mix_f32 v61, v9, v113, v61 op_sel:[0,1,0] op_sel_hi:[0,1,0]
	v_add_f32_dpp v12, v12, v12 row_ror:2 row_mask:0xf bank_mask:0xf bound_ctrl:1
	v_pk_fma_f32 v[48:49], v[28:29], v[66:67], v[6:7] op_sel_hi:[1,0,1]
	v_pk_fma_f32 v[50:51], v[30:31], v[66:67], v[8:9] op_sel_hi:[1,0,1]
	v_add_f32_dpp v12, v12, v12 row_ror:4 row_mask:0xf bank_mask:0xf bound_ctrl:1
	s_nop 1
	s_nop 0
	v_add_f32_dpp v12, v12, v12 row_ror:8 row_mask:0xf bank_mask:0xf bound_ctrl:1
	v_pk_fma_f32 v[6:7], v[24:25], v[12:13], v[48:49] op_sel_hi:[1,0,1] neg_lo:[1,0,0] neg_hi:[1,0,0]
	v_pk_fma_f32 v[8:9], v[26:27], v[12:13], v[50:51] op_sel_hi:[1,0,1] neg_lo:[1,0,0] neg_hi:[1,0,0]
	ds_read_b128 v[110:113], v10 offset:19712
	ds_read_b128 v[106:109], v10 offset:19456
	ds_read_b128 v[118:121], v10 offset:20224
	ds_read_b128 v[114:117], v10 offset:19968
	ds_read_b128 v[70:73], v11 offset:1280
	v_fma_mix_f32 v12, v6, v36, v180 op_sel_hi:[0,1,0]
	v_fma_mix_f32 v12, v7, v36, v12 op_sel:[0,1,0] op_sel_hi:[0,1,0]
	v_fma_mix_f32 v12, v8, v37, v12 op_sel_hi:[0,1,0]
	v_fma_mix_f32 v12, v9, v37, v12 op_sel:[0,1,0] op_sel_hi:[0,1,0]
	v_fma_mix_f32 v122, v6, v22, v180 op_sel_hi:[0,1,0]
	v_fma_mix_f32 v122, v7, v22, v122 op_sel:[0,1,0] op_sel_hi:[0,1,0]
	v_add_f32_dpp v12, v12, v12 row_ror:1 row_mask:0xf bank_mask:0xf bound_ctrl:1
	v_fma_mix_f32 v122, v8, v23, v122 op_sel_hi:[0,1,0]
	v_fma_mix_f32 v122, v9, v23, v122 op_sel:[0,1,0] op_sel_hi:[0,1,0]
	v_add_f32_dpp v12, v12, v12 row_ror:2 row_mask:0xf bank_mask:0xf bound_ctrl:1
	v_pk_fma_f32 v[48:49], v[44:45], v[66:67], v[6:7] op_sel:[0,1,0]
	v_pk_fma_f32 v[50:51], v[46:47], v[66:67], v[8:9] op_sel:[0,1,0]
	v_add_f32_dpp v12, v12, v12 row_ror:4 row_mask:0xf bank_mask:0xf bound_ctrl:1
	v_add_f32_dpp v83, v83, v83 row_ror:8 row_mask:0xf bank_mask:0xc
	v_add_f32_dpp v83, v52, v52 row_ror:8 row_mask:0xf bank_mask:0x3
	v_add_f32_dpp v100, v100, v100 row_ror:8 row_mask:0xf bank_mask:0xc
	v_add_f32_dpp v12, v12, v12 row_ror:8 row_mask:0xf bank_mask:0xf bound_ctrl:1
	v_pk_fma_f32 v[6:7], v[40:41], v[12:13], v[48:49] op_sel_hi:[1,0,1] neg_lo:[1,0,0] neg_hi:[1,0,0]
	v_pk_fma_f32 v[8:9], v[42:43], v[12:13], v[50:51] op_sel_hi:[1,0,1] neg_lo:[1,0,0] neg_hi:[1,0,0]
	ds_read_b128 v[20:23], v10 offset:20736
	ds_read_b128 v[28:31], v10 offset:21248
	ds_read_b128 v[24:27], v10 offset:20992
	s_waitcnt lgkmcnt(4)
	s_nop 0
	v_fma_mix_f32 v12, v6, v88, v180 op_sel_hi:[0,1,0]
	v_fma_mix_f32 v12, v7, v88, v12 op_sel:[0,1,0] op_sel_hi:[0,1,0]
	v_fma_mix_f32 v12, v8, v89, v12 op_sel_hi:[0,1,0]
	v_fma_mix_f32 v12, v9, v89, v12 op_sel:[0,1,0] op_sel_hi:[0,1,0]
	v_fma_mix_f32 v123, v6, v38, v180 op_sel_hi:[0,1,0]
	v_fma_mix_f32 v123, v7, v38, v123 op_sel:[0,1,0] op_sel_hi:[0,1,0]
	v_add_f32_dpp v12, v12, v12 row_ror:1 row_mask:0xf bank_mask:0xf bound_ctrl:1
	v_fma_mix_f32 v123, v8, v39, v123 op_sel_hi:[0,1,0]
	v_fma_mix_f32 v123, v9, v39, v123 op_sel:[0,1,0] op_sel_hi:[0,1,0]
	v_add_f32_dpp v12, v12, v12 row_ror:2 row_mask:0xf bank_mask:0xf bound_ctrl:1
	v_pk_fma_f32 v[48:49], v[96:97], v[68:69], v[6:7] op_sel_hi:[1,0,1]
	v_pk_fma_f32 v[50:51], v[98:99], v[68:69], v[8:9] op_sel_hi:[1,0,1]
	v_add_f32_dpp v12, v12, v12 row_ror:4 row_mask:0xf bank_mask:0xf bound_ctrl:1
	v_add_f32_dpp v100, v53, v53 row_ror:8 row_mask:0xf bank_mask:0x3
	v_add_f32_dpp v101, v101, v101 row_ror:8 row_mask:0xf bank_mask:0xc
	v_add_f32_dpp v101, v54, v54 row_ror:8 row_mask:0xf bank_mask:0x3
	v_add_f32_dpp v12, v12, v12 row_ror:8 row_mask:0xf bank_mask:0xf bound_ctrl:1
	v_pk_fma_f32 v[6:7], v[92:93], v[12:13], v[48:49] op_sel_hi:[1,0,1] neg_lo:[1,0,0] neg_hi:[1,0,0]
	v_pk_fma_f32 v[8:9], v[94:95], v[12:13], v[50:51] op_sel_hi:[1,0,1] neg_lo:[1,0,0] neg_hi:[1,0,0]
	ds_read_b128 v[36:39], v10 offset:21760
	ds_read_b128 v[44:47], v10 offset:22272
	ds_read_b128 v[40:43], v10 offset:22016
	v_fma_mix_f32 v12, v6, v110, v180 op_sel_hi:[0,1,0]
	v_fma_mix_f32 v12, v7, v110, v12 op_sel:[0,1,0] op_sel_hi:[0,1,0]
	v_fma_mix_f32 v12, v8, v111, v12 op_sel_hi:[0,1,0]
	v_fma_mix_f32 v12, v9, v111, v12 op_sel:[0,1,0] op_sel_hi:[0,1,0]
	v_fma_mix_f32 v124, v6, v90, v180 op_sel_hi:[0,1,0]
	v_fma_mix_f32 v124, v7, v90, v124 op_sel:[0,1,0] op_sel_hi:[0,1,0]
	v_add_f32_dpp v12, v12, v12 row_ror:1 row_mask:0xf bank_mask:0xf bound_ctrl:1
	v_fma_mix_f32 v124, v8, v91, v124 op_sel_hi:[0,1,0]
	v_fma_mix_f32 v124, v9, v91, v124 op_sel:[0,1,0] op_sel_hi:[0,1,0]
	v_add_f32_dpp v12, v12, v12 row_ror:2 row_mask:0xf bank_mask:0xf bound_ctrl:1
	v_pk_fma_f32 v[48:49], v[118:119], v[68:69], v[6:7] op_sel:[0,1,0]
	v_pk_fma_f32 v[50:51], v[120:121], v[68:69], v[8:9] op_sel:[0,1,0]
	v_add_f32_dpp v12, v12, v12 row_ror:4 row_mask:0xf bank_mask:0xf bound_ctrl:1
	v_add_f32_dpp v102, v102, v102 row_ror:8 row_mask:0xf bank_mask:0xc
	v_add_f32_dpp v102, v55, v55 row_ror:8 row_mask:0xf bank_mask:0x3
	v_add_f32_dpp v103, v103, v103 row_ror:8 row_mask:0xf bank_mask:0xc
	v_add_f32_dpp v12, v12, v12 row_ror:8 row_mask:0xf bank_mask:0xf bound_ctrl:1
	v_pk_fma_f32 v[6:7], v[114:115], v[12:13], v[48:49] op_sel_hi:[1,0,1] neg_lo:[1,0,0] neg_hi:[1,0,0]
	v_pk_fma_f32 v[8:9], v[116:117], v[12:13], v[50:51] op_sel_hi:[1,0,1] neg_lo:[1,0,0] neg_hi:[1,0,0]
	v_pk_mul_f32 v[6:7], v[6:7], v[106:107]
	v_pk_mul_f32 v[8:9], v[8:9], v[108:109]
	ds_read_b128 v[88:91], v10 offset:22784
	ds_read_b128 v[96:99], v10 offset:23296
	ds_read_b128 v[92:95], v10 offset:23040
	s_waitcnt lgkmcnt(3)
	s_nop 0
	v_fma_mix_f32 v12, v6, v20, v180 op_sel_hi:[0,1,0]
	v_fma_mix_f32 v12, v7, v20, v12 op_sel:[0,1,0] op_sel_hi:[0,1,0]
	v_fma_mix_f32 v12, v8, v21, v12 op_sel_hi:[0,1,0]
	v_fma_mix_f32 v12, v9, v21, v12 op_sel:[0,1,0] op_sel_hi:[0,1,0]
	v_fma_mix_f32 v125, v6, v112, v180 op_sel_hi:[0,1,0]
	v_fma_mix_f32 v125, v7, v112, v125 op_sel:[0,1,0] op_sel_hi:[0,1,0]
	v_add_f32_dpp v12, v12, v12 row_ror:1 row_mask:0xf bank_mask:0xf bound_ctrl:1
	v_fma_mix_f32 v125, v8, v113, v125 op_sel_hi:[0,1,0]
	v_fma_mix_f32 v125, v9, v113, v125 op_sel:[0,1,0] op_sel_hi:[0,1,0]
	v_add_f32_dpp v12, v12, v12 row_ror:2 row_mask:0xf bank_mask:0xf bound_ctrl:1
	v_pk_fma_f32 v[48:49], v[28:29], v[70:71], v[6:7] op_sel_hi:[1,0,1]
	v_pk_fma_f32 v[50:51], v[30:31], v[70:71], v[8:9] op_sel_hi:[1,0,1]
	v_add_f32_dpp v12, v12, v12 row_ror:4 row_mask:0xf bank_mask:0xf bound_ctrl:1
	v_add_f32_dpp v103, v56, v56 row_ror:8 row_mask:0xf bank_mask:0x3
	v_add_f32_dpp v104, v104, v104 row_ror:8 row_mask:0xf bank_mask:0xc
	v_add_f32_dpp v104, v57, v57 row_ror:8 row_mask:0xf bank_mask:0x3
	v_add_f32_dpp v12, v12, v12 row_ror:8 row_mask:0xf bank_mask:0xf bound_ctrl:1
	v_pk_fma_f32 v[6:7], v[24:25], v[12:13], v[48:49] op_sel_hi:[1,0,1] neg_lo:[1,0,0] neg_hi:[1,0,0]
	v_pk_fma_f32 v[8:9], v[26:27], v[12:13], v[50:51] op_sel_hi:[1,0,1] neg_lo:[1,0,0] neg_hi:[1,0,0]
	ds_read_b128 v[110:113], v10 offset:23808
	ds_read_b128 v[106:109], v10 offset:23552
	ds_read_b128 v[118:121], v10 offset:24320
	ds_read_b128 v[114:117], v10 offset:24064
	ds_read_b128 v[66:69], v11 offset:1536
	v_fma_mix_f32 v12, v6, v36, v180 op_sel_hi:[0,1,0]
	v_fma_mix_f32 v12, v7, v36, v12 op_sel:[0,1,0] op_sel_hi:[0,1,0]
	v_fma_mix_f32 v12, v8, v37, v12 op_sel_hi:[0,1,0]
	v_fma_mix_f32 v12, v9, v37, v12 op_sel:[0,1,0] op_sel_hi:[0,1,0]
	v_fma_mix_f32 v126, v6, v22, v180 op_sel_hi:[0,1,0]
	v_fma_mix_f32 v126, v7, v22, v126 op_sel:[0,1,0] op_sel_hi:[0,1,0]
	v_add_f32_dpp v12, v12, v12 row_ror:1 row_mask:0xf bank_mask:0xf bound_ctrl:1
	v_fma_mix_f32 v126, v8, v23, v126 op_sel_hi:[0,1,0]
	v_fma_mix_f32 v126, v9, v23, v126 op_sel:[0,1,0] op_sel_hi:[0,1,0]
	v_add_f32_dpp v12, v12, v12 row_ror:2 row_mask:0xf bank_mask:0xf bound_ctrl:1
	v_pk_fma_f32 v[48:49], v[44:45], v[70:71], v[6:7] op_sel:[0,1,0]
	v_pk_fma_f32 v[50:51], v[46:47], v[70:71], v[8:9] op_sel:[0,1,0]
	v_add_f32_dpp v12, v12, v12 row_ror:4 row_mask:0xf bank_mask:0xf bound_ctrl:1
	v_add_f32_dpp v105, v105, v105 row_ror:8 row_mask:0xf bank_mask:0xc
	v_add_f32_dpp v105, v81, v81 row_ror:8 row_mask:0xf bank_mask:0x3
	v_add_f32_dpp v12, v12, v12 row_ror:8 row_mask:0xf bank_mask:0xf bound_ctrl:1
	v_pk_fma_f32 v[6:7], v[40:41], v[12:13], v[48:49] op_sel_hi:[1,0,1] neg_lo:[1,0,0] neg_hi:[1,0,0]
	v_pk_fma_f32 v[8:9], v[42:43], v[12:13], v[50:51] op_sel_hi:[1,0,1] neg_lo:[1,0,0] neg_hi:[1,0,0]
	ds_read_b128 v[20:23], v10 offset:24832
	ds_read_b128 v[28:31], v10 offset:25344
	ds_read_b128 v[24:27], v10 offset:25088
	s_waitcnt lgkmcnt(4)
	s_nop 0
	v_fma_mix_f32 v12, v6, v88, v180 op_sel_hi:[0,1,0]
	v_fma_mix_f32 v12, v7, v88, v12 op_sel:[0,1,0] op_sel_hi:[0,1,0]
	v_fma_mix_f32 v12, v8, v89, v12 op_sel_hi:[0,1,0]
	v_fma_mix_f32 v12, v9, v89, v12 op_sel:[0,1,0] op_sel_hi:[0,1,0]
	v_fma_mix_f32 v127, v6, v38, v180 op_sel_hi:[0,1,0]
	v_fma_mix_f32 v127, v7, v38, v127 op_sel:[0,1,0] op_sel_hi:[0,1,0]
	v_add_f32_dpp v12, v12, v12 row_ror:1 row_mask:0xf bank_mask:0xf bound_ctrl:1
	v_fma_mix_f32 v127, v8, v39, v127 op_sel_hi:[0,1,0]
	v_fma_mix_f32 v127, v9, v39, v127 op_sel:[0,1,0] op_sel_hi:[0,1,0]
	v_add_f32_dpp v12, v12, v12 row_ror:2 row_mask:0xf bank_mask:0xf bound_ctrl:1
	v_pk_fma_f32 v[48:49], v[96:97], v[72:73], v[6:7] op_sel_hi:[1,0,1]
	v_pk_fma_f32 v[50:51], v[98:99], v[72:73], v[8:9] op_sel_hi:[1,0,1]
	v_add_f32_dpp v12, v12, v12 row_ror:4 row_mask:0xf bank_mask:0xf bound_ctrl:1
	v_add_f32_dpp v61, v61, v61 row_ror:8 row_mask:0xf bank_mask:0xc
	v_add_f32_dpp v61, v82, v82 row_ror:8 row_mask:0xf bank_mask:0x3
	v_add_f32_dpp v12, v12, v12 row_ror:8 row_mask:0xf bank_mask:0xf bound_ctrl:1
	v_pk_fma_f32 v[6:7], v[92:93], v[12:13], v[48:49] op_sel_hi:[1,0,1] neg_lo:[1,0,0] neg_hi:[1,0,0]
	v_pk_fma_f32 v[8:9], v[94:95], v[12:13], v[50:51] op_sel_hi:[1,0,1] neg_lo:[1,0,0] neg_hi:[1,0,0]
	ds_read_b128 v[36:39], v10 offset:25856
	ds_read_b128 v[44:47], v10 offset:26368
	ds_read_b128 v[40:43], v10 offset:26112
	v_fma_mix_f32 v12, v6, v110, v180 op_sel_hi:[0,1,0]
	v_fma_mix_f32 v12, v7, v110, v12 op_sel:[0,1,0] op_sel_hi:[0,1,0]
	v_fma_mix_f32 v12, v8, v111, v12 op_sel_hi:[0,1,0]
	v_fma_mix_f32 v12, v9, v111, v12 op_sel:[0,1,0] op_sel_hi:[0,1,0]
	v_fma_mix_f32 v128, v6, v90, v180 op_sel_hi:[0,1,0]
	v_fma_mix_f32 v128, v7, v90, v128 op_sel:[0,1,0] op_sel_hi:[0,1,0]
	v_add_f32_dpp v12, v12, v12 row_ror:1 row_mask:0xf bank_mask:0xf bound_ctrl:1
	v_fma_mix_f32 v128, v8, v91, v128 op_sel_hi:[0,1,0]
	v_fma_mix_f32 v128, v9, v91, v128 op_sel:[0,1,0] op_sel_hi:[0,1,0]
	v_add_f32_dpp v12, v12, v12 row_ror:2 row_mask:0xf bank_mask:0xf bound_ctrl:1
	v_pk_fma_f32 v[48:49], v[118:119], v[72:73], v[6:7] op_sel:[0,1,0]
	v_pk_fma_f32 v[50:51], v[120:121], v[72:73], v[8:9] op_sel:[0,1,0]
	v_add_f32_dpp v12, v12, v12 row_ror:4 row_mask:0xf bank_mask:0xf bound_ctrl:1
	v_add_f32_dpp v103, v103, v103 row_ror:4 row_mask:0xf bank_mask:0xa
	v_add_f32_dpp v103, v83, v83 row_ror:12 row_mask:0xf bank_mask:0x5
	v_add_f32_dpp v104, v104, v104 row_ror:4 row_mask:0xf bank_mask:0xa
	v_add_f32_dpp v12, v12, v12 row_ror:8 row_mask:0xf bank_mask:0xf bound_ctrl:1
	v_pk_fma_f32 v[6:7], v[114:115], v[12:13], v[48:49] op_sel_hi:[1,0,1] neg_lo:[1,0,0] neg_hi:[1,0,0]
	v_pk_fma_f32 v[8:9], v[116:117], v[12:13], v[50:51] op_sel_hi:[1,0,1] neg_lo:[1,0,0] neg_hi:[1,0,0]
	v_pk_mul_f32 v[6:7], v[6:7], v[106:107]
	v_pk_mul_f32 v[8:9], v[8:9], v[108:109]
	ds_read_b128 v[88:91], v10 offset:26880
	ds_read_b128 v[96:99], v10 offset:27392
	ds_read_b128 v[92:95], v10 offset:27136
	s_waitcnt lgkmcnt(3)
	s_nop 0
	v_fma_mix_f32 v12, v6, v20, v180 op_sel_hi:[0,1,0]
	v_fma_mix_f32 v12, v7, v20, v12 op_sel:[0,1,0] op_sel_hi:[0,1,0]
	v_fma_mix_f32 v12, v8, v21, v12 op_sel_hi:[0,1,0]
	v_fma_mix_f32 v12, v9, v21, v12 op_sel:[0,1,0] op_sel_hi:[0,1,0]
	v_fma_mix_f32 v129, v6, v112, v180 op_sel_hi:[0,1,0]
	v_fma_mix_f32 v129, v7, v112, v129 op_sel:[0,1,0] op_sel_hi:[0,1,0]
	v_add_f32_dpp v12, v12, v12 row_ror:1 row_mask:0xf bank_mask:0xf bound_ctrl:1
	v_fma_mix_f32 v129, v8, v113, v129 op_sel_hi:[0,1,0]
	v_fma_mix_f32 v129, v9, v113, v129 op_sel:[0,1,0] op_sel_hi:[0,1,0]
	v_add_f32_dpp v12, v12, v12 row_ror:2 row_mask:0xf bank_mask:0xf bound_ctrl:1
	v_pk_fma_f32 v[48:49], v[28:29], v[66:67], v[6:7] op_sel_hi:[1,0,1]
	v_pk_fma_f32 v[50:51], v[30:31], v[66:67], v[8:9] op_sel_hi:[1,0,1]
	v_add_f32_dpp v12, v12, v12 row_ror:4 row_mask:0xf bank_mask:0xf bound_ctrl:1
	v_add_f32_dpp v104, v100, v100 row_ror:12 row_mask:0xf bank_mask:0x5
	v_add_f32_dpp v105, v105, v105 row_ror:4 row_mask:0xf bank_mask:0xa
	v_add_f32_dpp v105, v101, v101 row_ror:12 row_mask:0xf bank_mask:0x5
	v_add_f32_dpp v12, v12, v12 row_ror:8 row_mask:0xf bank_mask:0xf bound_ctrl:1
	v_pk_fma_f32 v[6:7], v[24:25], v[12:13], v[48:49] op_sel_hi:[1,0,1] neg_lo:[1,0,0] neg_hi:[1,0,0]
	v_pk_fma_f32 v[8:9], v[26:27], v[12:13], v[50:51] op_sel_hi:[1,0,1] neg_lo:[1,0,0] neg_hi:[1,0,0]
	ds_read_b128 v[110:113], v10 offset:27904
	ds_read_b128 v[106:109], v10 offset:27648
	ds_read_b128 v[118:121], v10 offset:28416
	ds_read_b128 v[114:117], v10 offset:28160
	ds_read_b128 v[70:73], v11 offset:1792
	v_fma_mix_f32 v12, v6, v36, v180 op_sel_hi:[0,1,0]
	v_fma_mix_f32 v12, v7, v36, v12 op_sel:[0,1,0] op_sel_hi:[0,1,0]
	v_fma_mix_f32 v12, v8, v37, v12 op_sel_hi:[0,1,0]
	v_fma_mix_f32 v12, v9, v37, v12 op_sel:[0,1,0] op_sel_hi:[0,1,0]
	v_fma_mix_f32 v130, v6, v22, v180 op_sel_hi:[0,1,0]
	v_fma_mix_f32 v130, v7, v22, v130 op_sel:[0,1,0] op_sel_hi:[0,1,0]
	v_add_f32_dpp v12, v12, v12 row_ror:1 row_mask:0xf bank_mask:0xf bound_ctrl:1
	v_fma_mix_f32 v130, v8, v23, v130 op_sel_hi:[0,1,0]
	v_fma_mix_f32 v130, v9, v23, v130 op_sel:[0,1,0] op_sel_hi:[0,1,0]
	v_add_f32_dpp v12, v12, v12 row_ror:2 row_mask:0xf bank_mask:0xf bound_ctrl:1
	v_pk_fma_f32 v[48:49], v[44:45], v[66:67], v[6:7] op_sel:[0,1,0]
	v_pk_fma_f32 v[50:51], v[46:47], v[66:67], v[8:9] op_sel:[0,1,0]
	v_add_f32_dpp v12, v12, v12 row_ror:4 row_mask:0xf bank_mask:0xf bound_ctrl:1
	v_add_f32_dpp v61, v61, v61 row_ror:4 row_mask:0xf bank_mask:0xa
	v_add_f32_dpp v61, v102, v102 row_ror:12 row_mask:0xf bank_mask:0x5
	v_add_f32_dpp v12, v12, v12 row_ror:8 row_mask:0xf bank_mask:0xf bound_ctrl:1
	v_pk_fma_f32 v[6:7], v[40:41], v[12:13], v[48:49] op_sel_hi:[1,0,1] neg_lo:[1,0,0] neg_hi:[1,0,0]
	v_pk_fma_f32 v[8:9], v[42:43], v[12:13], v[50:51] op_sel_hi:[1,0,1] neg_lo:[1,0,0] neg_hi:[1,0,0]
	ds_read_b128 v[20:23], v10 offset:28928
	ds_read_b128 v[28:31], v10 offset:29440
	ds_read_b128 v[24:27], v10 offset:29184
	s_waitcnt lgkmcnt(4)
	s_nop 0
	v_fma_mix_f32 v12, v6, v88, v180 op_sel_hi:[0,1,0]
	v_fma_mix_f32 v12, v7, v88, v12 op_sel:[0,1,0] op_sel_hi:[0,1,0]
	v_fma_mix_f32 v12, v8, v89, v12 op_sel_hi:[0,1,0]
	v_fma_mix_f32 v12, v9, v89, v12 op_sel:[0,1,0] op_sel_hi:[0,1,0]
	v_fma_mix_f32 v131, v6, v38, v180 op_sel_hi:[0,1,0]
	v_fma_mix_f32 v131, v7, v38, v131 op_sel:[0,1,0] op_sel_hi:[0,1,0]
	v_add_f32_dpp v12, v12, v12 row_ror:1 row_mask:0xf bank_mask:0xf bound_ctrl:1
	v_fma_mix_f32 v131, v8, v39, v131 op_sel_hi:[0,1,0]
	v_fma_mix_f32 v131, v9, v39, v131 op_sel:[0,1,0] op_sel_hi:[0,1,0]
	v_add_f32_dpp v12, v12, v12 row_ror:2 row_mask:0xf bank_mask:0xf bound_ctrl:1
	v_pk_fma_f32 v[48:49], v[96:97], v[68:69], v[6:7] op_sel_hi:[1,0,1]
	v_pk_fma_f32 v[50:51], v[98:99], v[68:69], v[8:9] op_sel_hi:[1,0,1]
	v_add_f32_dpp v12, v12, v12 row_ror:4 row_mask:0xf bank_mask:0xf bound_ctrl:1
	v_cndmask_b32_e64 v62, v105, v103, s[38:39]
	v_cndmask_b32_e64 v63, v103, v105, s[38:39]
	v_add_f32_dpp v12, v12, v12 row_ror:8 row_mask:0xf bank_mask:0xf bound_ctrl:1
	v_pk_fma_f32 v[6:7], v[92:93], v[12:13], v[48:49] op_sel_hi:[1,0,1] neg_lo:[1,0,0] neg_hi:[1,0,0]
	v_pk_fma_f32 v[8:9], v[94:95], v[12:13], v[50:51] op_sel_hi:[1,0,1] neg_lo:[1,0,0] neg_hi:[1,0,0]
	ds_read_b128 v[36:39], v10 offset:29952
	ds_read_b128 v[44:47], v10 offset:30464
	ds_read_b128 v[40:43], v10 offset:30208
	v_fma_mix_f32 v12, v6, v110, v180 op_sel_hi:[0,1,0]
	v_fma_mix_f32 v12, v7, v110, v12 op_sel:[0,1,0] op_sel_hi:[0,1,0]
	v_fma_mix_f32 v12, v8, v111, v12 op_sel_hi:[0,1,0]
	v_fma_mix_f32 v12, v9, v111, v12 op_sel:[0,1,0] op_sel_hi:[0,1,0]
	v_fma_mix_f32 v132, v6, v90, v180 op_sel_hi:[0,1,0]
	v_fma_mix_f32 v132, v7, v90, v132 op_sel:[0,1,0] op_sel_hi:[0,1,0]
	v_add_f32_dpp v12, v12, v12 row_ror:1 row_mask:0xf bank_mask:0xf bound_ctrl:1
	v_fma_mix_f32 v132, v8, v91, v132 op_sel_hi:[0,1,0]
	v_fma_mix_f32 v132, v9, v91, v132 op_sel:[0,1,0] op_sel_hi:[0,1,0]
	v_add_f32_dpp v12, v12, v12 row_ror:2 row_mask:0xf bank_mask:0xf bound_ctrl:1
	v_pk_fma_f32 v[48:49], v[118:119], v[68:69], v[6:7] op_sel:[0,1,0]
	v_pk_fma_f32 v[50:51], v[120:121], v[68:69], v[8:9] op_sel:[0,1,0]
	v_add_f32_dpp v12, v12, v12 row_ror:4 row_mask:0xf bank_mask:0xf bound_ctrl:1
	v_cndmask_b32_e64 v64, v61, v104, s[38:39]
	v_cndmask_b32_e64 v65, v104, v61, s[38:39]
	v_add_f32_dpp v12, v12, v12 row_ror:8 row_mask:0xf bank_mask:0xf bound_ctrl:1
	v_pk_fma_f32 v[6:7], v[114:115], v[12:13], v[48:49] op_sel_hi:[1,0,1] neg_lo:[1,0,0] neg_hi:[1,0,0]
	v_pk_fma_f32 v[8:9], v[116:117], v[12:13], v[50:51] op_sel_hi:[1,0,1] neg_lo:[1,0,0] neg_hi:[1,0,0]
	v_pk_mul_f32 v[6:7], v[6:7], v[106:107]
	v_pk_mul_f32 v[8:9], v[8:9], v[108:109]
	ds_read_b128 v[88:91], v10 offset:30976
	ds_read_b128 v[96:99], v10 offset:31488
	ds_read_b128 v[92:95], v10 offset:31232
	s_waitcnt lgkmcnt(3)
	s_nop 0
	v_fma_mix_f32 v12, v6, v20, v180 op_sel_hi:[0,1,0]
	v_fma_mix_f32 v12, v7, v20, v12 op_sel:[0,1,0] op_sel_hi:[0,1,0]
	v_fma_mix_f32 v12, v8, v21, v12 op_sel_hi:[0,1,0]
	v_fma_mix_f32 v12, v9, v21, v12 op_sel:[0,1,0] op_sel_hi:[0,1,0]
	v_fma_mix_f32 v133, v6, v112, v180 op_sel_hi:[0,1,0]
	v_fma_mix_f32 v133, v7, v112, v133 op_sel:[0,1,0] op_sel_hi:[0,1,0]
	v_add_f32_dpp v12, v12, v12 row_ror:1 row_mask:0xf bank_mask:0xf bound_ctrl:1
	v_fma_mix_f32 v133, v8, v113, v133 op_sel_hi:[0,1,0]
	v_fma_mix_f32 v133, v9, v113, v133 op_sel:[0,1,0] op_sel_hi:[0,1,0]
	v_add_f32_dpp v12, v12, v12 row_ror:2 row_mask:0xf bank_mask:0xf bound_ctrl:1
	v_pk_fma_f32 v[48:49], v[28:29], v[70:71], v[6:7] op_sel_hi:[1,0,1]
	v_pk_fma_f32 v[50:51], v[30:31], v[70:71], v[8:9] op_sel_hi:[1,0,1]
	v_add_f32_dpp v12, v12, v12 row_ror:4 row_mask:0xf bank_mask:0xf bound_ctrl:1
	v_add_f32_dpp v62, v63, v62 quad_perm:[2,3,0,1] row_mask:0xf bank_mask:0xf bound_ctrl:1
	v_add_f32_dpp v63, v65, v64 quad_perm:[2,3,0,1] row_mask:0xf bank_mask:0xf bound_ctrl:1
	v_add_f32_dpp v12, v12, v12 row_ror:8 row_mask:0xf bank_mask:0xf bound_ctrl:1
	v_pk_fma_f32 v[6:7], v[24:25], v[12:13], v[48:49] op_sel_hi:[1,0,1] neg_lo:[1,0,0] neg_hi:[1,0,0]
	v_pk_fma_f32 v[8:9], v[26:27], v[12:13], v[50:51] op_sel_hi:[1,0,1] neg_lo:[1,0,0] neg_hi:[1,0,0]
	ds_read_b128 v[110:113], v10 offset:32000
	ds_read_b128 v[106:109], v10 offset:31744
	ds_read_b128 v[118:121], v10 offset:32512
	ds_read_b128 v[114:117], v10 offset:32256
	ds_read_b128 v[66:69], v11 offset:2048
	v_fma_mix_f32 v12, v6, v36, v180 op_sel_hi:[0,1,0]
	v_fma_mix_f32 v12, v7, v36, v12 op_sel:[0,1,0] op_sel_hi:[0,1,0]
	v_fma_mix_f32 v12, v8, v37, v12 op_sel_hi:[0,1,0]
	v_fma_mix_f32 v12, v9, v37, v12 op_sel:[0,1,0] op_sel_hi:[0,1,0]
	v_fma_mix_f32 v134, v6, v22, v180 op_sel_hi:[0,1,0]
	v_fma_mix_f32 v134, v7, v22, v134 op_sel:[0,1,0] op_sel_hi:[0,1,0]
	v_add_f32_dpp v12, v12, v12 row_ror:1 row_mask:0xf bank_mask:0xf bound_ctrl:1
	v_fma_mix_f32 v134, v8, v23, v134 op_sel_hi:[0,1,0]
	v_fma_mix_f32 v134, v9, v23, v134 op_sel:[0,1,0] op_sel_hi:[0,1,0]
	v_add_f32_dpp v12, v12, v12 row_ror:2 row_mask:0xf bank_mask:0xf bound_ctrl:1
	v_pk_fma_f32 v[48:49], v[44:45], v[70:71], v[6:7] op_sel:[0,1,0]
	v_pk_fma_f32 v[50:51], v[46:47], v[70:71], v[8:9] op_sel:[0,1,0]
	v_add_f32_dpp v12, v12, v12 row_ror:4 row_mask:0xf bank_mask:0xf bound_ctrl:1
	v_cndmask_b32_e64 v65, v63, v62, s[40:41]
	v_cndmask_b32_e64 v62, v62, v63, s[40:41]
	v_add_f32_dpp v12, v12, v12 row_ror:8 row_mask:0xf bank_mask:0xf bound_ctrl:1
	v_pk_fma_f32 v[6:7], v[40:41], v[12:13], v[48:49] op_sel_hi:[1,0,1] neg_lo:[1,0,0] neg_hi:[1,0,0]
	v_pk_fma_f32 v[8:9], v[42:43], v[12:13], v[50:51] op_sel_hi:[1,0,1] neg_lo:[1,0,0] neg_hi:[1,0,0]
	ds_read_b128 v[20:23], v10 offset:33024
	ds_read_b128 v[28:31], v10 offset:33536
	ds_read_b128 v[24:27], v10 offset:33280
	s_waitcnt lgkmcnt(4)
	s_nop 0
	v_fma_mix_f32 v12, v6, v88, v180 op_sel_hi:[0,1,0]
	v_fma_mix_f32 v12, v7, v88, v12 op_sel:[0,1,0] op_sel_hi:[0,1,0]
	v_fma_mix_f32 v12, v8, v89, v12 op_sel_hi:[0,1,0]
	v_fma_mix_f32 v12, v9, v89, v12 op_sel:[0,1,0] op_sel_hi:[0,1,0]
	v_fma_mix_f32 v135, v6, v38, v180 op_sel_hi:[0,1,0]
	v_fma_mix_f32 v135, v7, v38, v135 op_sel:[0,1,0] op_sel_hi:[0,1,0]
	v_add_f32_dpp v12, v12, v12 row_ror:1 row_mask:0xf bank_mask:0xf bound_ctrl:1
	v_fma_mix_f32 v135, v8, v39, v135 op_sel_hi:[0,1,0]
	v_fma_mix_f32 v135, v9, v39, v135 op_sel:[0,1,0] op_sel_hi:[0,1,0]
	v_add_f32_dpp v12, v12, v12 row_ror:2 row_mask:0xf bank_mask:0xf bound_ctrl:1
	v_pk_fma_f32 v[48:49], v[96:97], v[72:73], v[6:7] op_sel_hi:[1,0,1]
	v_pk_fma_f32 v[50:51], v[98:99], v[72:73], v[8:9] op_sel_hi:[1,0,1]
	v_add_f32_dpp v12, v12, v12 row_ror:4 row_mask:0xf bank_mask:0xf bound_ctrl:1
	v_add_f32_dpp v62, v62, v65 quad_perm:[1,0,3,2] row_mask:0xf bank_mask:0xf bound_ctrl:1
	v_cvt_pk_bf16_f32 v62, v62, v62
	v_add_f32_dpp v12, v12, v12 row_ror:8 row_mask:0xf bank_mask:0xf bound_ctrl:1
	v_pk_fma_f32 v[6:7], v[92:93], v[12:13], v[48:49] op_sel_hi:[1,0,1] neg_lo:[1,0,0] neg_hi:[1,0,0]
	v_pk_fma_f32 v[8:9], v[94:95], v[12:13], v[50:51] op_sel_hi:[1,0,1] neg_lo:[1,0,0] neg_hi:[1,0,0]
	ds_read_b128 v[36:39], v10 offset:34048
	ds_read_b128 v[44:47], v10 offset:34560
	ds_read_b128 v[40:43], v10 offset:34304
	v_fma_mix_f32 v12, v6, v110, v180 op_sel_hi:[0,1,0]
	v_fma_mix_f32 v12, v7, v110, v12 op_sel:[0,1,0] op_sel_hi:[0,1,0]
	v_fma_mix_f32 v12, v8, v111, v12 op_sel_hi:[0,1,0]
	v_fma_mix_f32 v12, v9, v111, v12 op_sel:[0,1,0] op_sel_hi:[0,1,0]
	v_fma_mix_f32 v136, v6, v90, v180 op_sel_hi:[0,1,0]
	v_fma_mix_f32 v136, v7, v90, v136 op_sel:[0,1,0] op_sel_hi:[0,1,0]
	v_add_f32_dpp v12, v12, v12 row_ror:1 row_mask:0xf bank_mask:0xf bound_ctrl:1
	v_fma_mix_f32 v136, v8, v91, v136 op_sel_hi:[0,1,0]
	v_fma_mix_f32 v136, v9, v91, v136 op_sel:[0,1,0] op_sel_hi:[0,1,0]
	v_add_f32_dpp v12, v12, v12 row_ror:2 row_mask:0xf bank_mask:0xf bound_ctrl:1
	v_pk_fma_f32 v[48:49], v[118:119], v[72:73], v[6:7] op_sel:[0,1,0]
	v_pk_fma_f32 v[50:51], v[120:121], v[72:73], v[8:9] op_sel:[0,1,0]
	v_add_f32_dpp v12, v12, v12 row_ror:4 row_mask:0xf bank_mask:0xf bound_ctrl:1
	global_store_short v[2:3], v62, off
	v_lshl_add_u64 v[2:3], v[2:3], 0, s[84:85]
	v_add_f32_dpp v12, v12, v12 row_ror:8 row_mask:0xf bank_mask:0xf bound_ctrl:1
	v_pk_fma_f32 v[6:7], v[114:115], v[12:13], v[48:49] op_sel_hi:[1,0,1] neg_lo:[1,0,0] neg_hi:[1,0,0]
	v_pk_fma_f32 v[8:9], v[116:117], v[12:13], v[50:51] op_sel_hi:[1,0,1] neg_lo:[1,0,0] neg_hi:[1,0,0]
	v_pk_mul_f32 v[6:7], v[6:7], v[106:107]
	v_pk_mul_f32 v[8:9], v[8:9], v[108:109]
	ds_read_b128 v[88:91], v10 offset:35072
	ds_read_b128 v[96:99], v10 offset:35584
	ds_read_b128 v[92:95], v10 offset:35328
	s_waitcnt lgkmcnt(3)
	s_nop 0
	v_fma_mix_f32 v12, v6, v20, v180 op_sel_hi:[0,1,0]
	v_fma_mix_f32 v12, v7, v20, v12 op_sel:[0,1,0] op_sel_hi:[0,1,0]
	v_fma_mix_f32 v12, v8, v21, v12 op_sel_hi:[0,1,0]
	v_fma_mix_f32 v12, v9, v21, v12 op_sel:[0,1,0] op_sel_hi:[0,1,0]
	v_fma_mix_f32 v137, v6, v112, v180 op_sel_hi:[0,1,0]
	v_fma_mix_f32 v137, v7, v112, v137 op_sel:[0,1,0] op_sel_hi:[0,1,0]
	v_add_f32_dpp v12, v12, v12 row_ror:1 row_mask:0xf bank_mask:0xf bound_ctrl:1
	v_fma_mix_f32 v137, v8, v113, v137 op_sel_hi:[0,1,0]
	v_fma_mix_f32 v137, v9, v113, v137 op_sel:[0,1,0] op_sel_hi:[0,1,0]
	v_add_f32_dpp v12, v12, v12 row_ror:2 row_mask:0xf bank_mask:0xf bound_ctrl:1
	v_pk_fma_f32 v[48:49], v[28:29], v[66:67], v[6:7] op_sel_hi:[1,0,1]
	v_pk_fma_f32 v[50:51], v[30:31], v[66:67], v[8:9] op_sel_hi:[1,0,1]
	v_add_f32_dpp v12, v12, v12 row_ror:4 row_mask:0xf bank_mask:0xf bound_ctrl:1
	s_nop 1
	s_nop 0
	v_add_f32_dpp v12, v12, v12 row_ror:8 row_mask:0xf bank_mask:0xf bound_ctrl:1
	v_pk_fma_f32 v[6:7], v[24:25], v[12:13], v[48:49] op_sel_hi:[1,0,1] neg_lo:[1,0,0] neg_hi:[1,0,0]
	v_pk_fma_f32 v[8:9], v[26:27], v[12:13], v[50:51] op_sel_hi:[1,0,1] neg_lo:[1,0,0] neg_hi:[1,0,0]
	ds_read_b128 v[110:113], v10 offset:36096
	ds_read_b128 v[106:109], v10 offset:35840
	ds_read_b128 v[118:121], v10 offset:36608
	ds_read_b128 v[114:117], v10 offset:36352
	ds_read_b128 v[70:73], v11 offset:2304
	v_fma_mix_f32 v12, v6, v36, v180 op_sel_hi:[0,1,0]
	v_fma_mix_f32 v12, v7, v36, v12 op_sel:[0,1,0] op_sel_hi:[0,1,0]
	v_fma_mix_f32 v12, v8, v37, v12 op_sel_hi:[0,1,0]
	v_fma_mix_f32 v12, v9, v37, v12 op_sel:[0,1,0] op_sel_hi:[0,1,0]
	v_fma_mix_f32 v52, v6, v22, v180 op_sel_hi:[0,1,0]
	v_fma_mix_f32 v52, v7, v22, v52 op_sel:[0,1,0] op_sel_hi:[0,1,0]
	v_add_f32_dpp v12, v12, v12 row_ror:1 row_mask:0xf bank_mask:0xf bound_ctrl:1
	v_fma_mix_f32 v52, v8, v23, v52 op_sel_hi:[0,1,0]
	v_fma_mix_f32 v52, v9, v23, v52 op_sel:[0,1,0] op_sel_hi:[0,1,0]
	v_add_f32_dpp v12, v12, v12 row_ror:2 row_mask:0xf bank_mask:0xf bound_ctrl:1
	v_pk_fma_f32 v[48:49], v[44:45], v[66:67], v[6:7] op_sel:[0,1,0]
	v_pk_fma_f32 v[50:51], v[46:47], v[66:67], v[8:9] op_sel:[0,1,0]
	v_add_f32_dpp v12, v12, v12 row_ror:4 row_mask:0xf bank_mask:0xf bound_ctrl:1
	v_add_f32_dpp v130, v130, v130 row_ror:8 row_mask:0xf bank_mask:0xc
	v_add_f32_dpp v130, v122, v122 row_ror:8 row_mask:0xf bank_mask:0x3
	v_add_f32_dpp v131, v131, v131 row_ror:8 row_mask:0xf bank_mask:0xc
	v_add_f32_dpp v12, v12, v12 row_ror:8 row_mask:0xf bank_mask:0xf bound_ctrl:1
	v_pk_fma_f32 v[6:7], v[40:41], v[12:13], v[48:49] op_sel_hi:[1,0,1] neg_lo:[1,0,0] neg_hi:[1,0,0]
	v_pk_fma_f32 v[8:9], v[42:43], v[12:13], v[50:51] op_sel_hi:[1,0,1] neg_lo:[1,0,0] neg_hi:[1,0,0]
	ds_read_b128 v[20:23], v10 offset:37120
	ds_read_b128 v[28:31], v10 offset:37632
	ds_read_b128 v[24:27], v10 offset:37376
	s_waitcnt lgkmcnt(4)
	s_nop 0
	v_fma_mix_f32 v12, v6, v88, v180 op_sel_hi:[0,1,0]
	v_fma_mix_f32 v12, v7, v88, v12 op_sel:[0,1,0] op_sel_hi:[0,1,0]
	v_fma_mix_f32 v12, v8, v89, v12 op_sel_hi:[0,1,0]
	v_fma_mix_f32 v12, v9, v89, v12 op_sel:[0,1,0] op_sel_hi:[0,1,0]
	v_fma_mix_f32 v53, v6, v38, v180 op_sel_hi:[0,1,0]
	v_fma_mix_f32 v53, v7, v38, v53 op_sel:[0,1,0] op_sel_hi:[0,1,0]
	v_add_f32_dpp v12, v12, v12 row_ror:1 row_mask:0xf bank_mask:0xf bound_ctrl:1
	v_fma_mix_f32 v53, v8, v39, v53 op_sel_hi:[0,1,0]
	v_fma_mix_f32 v53, v9, v39, v53 op_sel:[0,1,0] op_sel_hi:[0,1,0]
	v_add_f32_dpp v12, v12, v12 row_ror:2 row_mask:0xf bank_mask:0xf bound_ctrl:1
	v_pk_fma_f32 v[48:49], v[96:97], v[68:69], v[6:7] op_sel_hi:[1,0,1]
	v_pk_fma_f32 v[50:51], v[98:99], v[68:69], v[8:9] op_sel_hi:[1,0,1]
	v_add_f32_dpp v12, v12, v12 row_ror:4 row_mask:0xf bank_mask:0xf bound_ctrl:1
	v_add_f32_dpp v131, v123, v123 row_ror:8 row_mask:0xf bank_mask:0x3
	v_add_f32_dpp v132, v132, v132 row_ror:8 row_mask:0xf bank_mask:0xc
	v_add_f32_dpp v132, v124, v124 row_ror:8 row_mask:0xf bank_mask:0x3
	v_add_f32_dpp v12, v12, v12 row_ror:8 row_mask:0xf bank_mask:0xf bound_ctrl:1
	v_pk_fma_f32 v[6:7], v[92:93], v[12:13], v[48:49] op_sel_hi:[1,0,1] neg_lo:[1,0,0] neg_hi:[1,0,0]
	v_pk_fma_f32 v[8:9], v[94:95], v[12:13], v[50:51] op_sel_hi:[1,0,1] neg_lo:[1,0,0] neg_hi:[1,0,0]
	ds_read_b128 v[36:39], v10 offset:38144
	ds_read_b128 v[44:47], v10 offset:38656
	ds_read_b128 v[40:43], v10 offset:38400
	v_fma_mix_f32 v12, v6, v110, v180 op_sel_hi:[0,1,0]
	v_fma_mix_f32 v12, v7, v110, v12 op_sel:[0,1,0] op_sel_hi:[0,1,0]
	v_fma_mix_f32 v12, v8, v111, v12 op_sel_hi:[0,1,0]
	v_fma_mix_f32 v12, v9, v111, v12 op_sel:[0,1,0] op_sel_hi:[0,1,0]
	v_fma_mix_f32 v54, v6, v90, v180 op_sel_hi:[0,1,0]
	v_fma_mix_f32 v54, v7, v90, v54 op_sel:[0,1,0] op_sel_hi:[0,1,0]
	v_add_f32_dpp v12, v12, v12 row_ror:1 row_mask:0xf bank_mask:0xf bound_ctrl:1
	v_fma_mix_f32 v54, v8, v91, v54 op_sel_hi:[0,1,0]
	v_fma_mix_f32 v54, v9, v91, v54 op_sel:[0,1,0] op_sel_hi:[0,1,0]
	v_add_f32_dpp v12, v12, v12 row_ror:2 row_mask:0xf bank_mask:0xf bound_ctrl:1
	v_pk_fma_f32 v[48:49], v[118:119], v[68:69], v[6:7] op_sel:[0,1,0]
	v_pk_fma_f32 v[50:51], v[120:121], v[68:69], v[8:9] op_sel:[0,1,0]
	v_add_f32_dpp v12, v12, v12 row_ror:4 row_mask:0xf bank_mask:0xf bound_ctrl:1
	v_add_f32_dpp v133, v133, v133 row_ror:8 row_mask:0xf bank_mask:0xc
	v_add_f32_dpp v133, v125, v125 row_ror:8 row_mask:0xf bank_mask:0x3
	v_add_f32_dpp v134, v134, v134 row_ror:8 row_mask:0xf bank_mask:0xc
	v_add_f32_dpp v12, v12, v12 row_ror:8 row_mask:0xf bank_mask:0xf bound_ctrl:1
	v_pk_fma_f32 v[6:7], v[114:115], v[12:13], v[48:49] op_sel_hi:[1,0,1] neg_lo:[1,0,0] neg_hi:[1,0,0]
	v_pk_fma_f32 v[8:9], v[116:117], v[12:13], v[50:51] op_sel_hi:[1,0,1] neg_lo:[1,0,0] neg_hi:[1,0,0]
	v_pk_mul_f32 v[6:7], v[6:7], v[106:107]
	v_pk_mul_f32 v[8:9], v[8:9], v[108:109]
	ds_read_b128 v[88:91], v10 offset:39168
	ds_read_b128 v[96:99], v10 offset:39680
	ds_read_b128 v[92:95], v10 offset:39424
	s_waitcnt lgkmcnt(3)
	s_nop 0
	v_fma_mix_f32 v12, v6, v20, v180 op_sel_hi:[0,1,0]
	v_fma_mix_f32 v12, v7, v20, v12 op_sel:[0,1,0] op_sel_hi:[0,1,0]
	v_fma_mix_f32 v12, v8, v21, v12 op_sel_hi:[0,1,0]
	v_fma_mix_f32 v12, v9, v21, v12 op_sel:[0,1,0] op_sel_hi:[0,1,0]
	v_fma_mix_f32 v55, v6, v112, v180 op_sel_hi:[0,1,0]
	v_fma_mix_f32 v55, v7, v112, v55 op_sel:[0,1,0] op_sel_hi:[0,1,0]
	v_add_f32_dpp v12, v12, v12 row_ror:1 row_mask:0xf bank_mask:0xf bound_ctrl:1
	v_fma_mix_f32 v55, v8, v113, v55 op_sel_hi:[0,1,0]
	v_fma_mix_f32 v55, v9, v113, v55 op_sel:[0,1,0] op_sel_hi:[0,1,0]
	v_add_f32_dpp v12, v12, v12 row_ror:2 row_mask:0xf bank_mask:0xf bound_ctrl:1
	v_pk_fma_f32 v[48:49], v[28:29], v[70:71], v[6:7] op_sel_hi:[1,0,1]
	v_pk_fma_f32 v[50:51], v[30:31], v[70:71], v[8:9] op_sel_hi:[1,0,1]
	v_add_f32_dpp v12, v12, v12 row_ror:4 row_mask:0xf bank_mask:0xf bound_ctrl:1
	v_add_f32_dpp v134, v126, v126 row_ror:8 row_mask:0xf bank_mask:0x3
	v_add_f32_dpp v135, v135, v135 row_ror:8 row_mask:0xf bank_mask:0xc
	v_add_f32_dpp v135, v127, v127 row_ror:8 row_mask:0xf bank_mask:0x3
	v_add_f32_dpp v12, v12, v12 row_ror:8 row_mask:0xf bank_mask:0xf bound_ctrl:1
	v_pk_fma_f32 v[6:7], v[24:25], v[12:13], v[48:49] op_sel_hi:[1,0,1] neg_lo:[1,0,0] neg_hi:[1,0,0]
	v_pk_fma_f32 v[8:9], v[26:27], v[12:13], v[50:51] op_sel_hi:[1,0,1] neg_lo:[1,0,0] neg_hi:[1,0,0]
	ds_read_b128 v[110:113], v10 offset:40192
	ds_read_b128 v[106:109], v10 offset:39936
	ds_read_b128 v[118:121], v10 offset:40704
	ds_read_b128 v[114:117], v10 offset:40448
	ds_read_b128 v[66:69], v11 offset:2560
	v_fma_mix_f32 v12, v6, v36, v180 op_sel_hi:[0,1,0]
	v_fma_mix_f32 v12, v7, v36, v12 op_sel:[0,1,0] op_sel_hi:[0,1,0]
	v_fma_mix_f32 v12, v8, v37, v12 op_sel_hi:[0,1,0]
	v_fma_mix_f32 v12, v9, v37, v12 op_sel:[0,1,0] op_sel_hi:[0,1,0]
	v_fma_mix_f32 v56, v6, v22, v180 op_sel_hi:[0,1,0]
	v_fma_mix_f32 v56, v7, v22, v56 op_sel:[0,1,0] op_sel_hi:[0,1,0]
	v_add_f32_dpp v12, v12, v12 row_ror:1 row_mask:0xf bank_mask:0xf bound_ctrl:1
	v_fma_mix_f32 v56, v8, v23, v56 op_sel_hi:[0,1,0]
	v_fma_mix_f32 v56, v9, v23, v56 op_sel:[0,1,0] op_sel_hi:[0,1,0]
	v_add_f32_dpp v12, v12, v12 row_ror:2 row_mask:0xf bank_mask:0xf bound_ctrl:1
	v_pk_fma_f32 v[48:49], v[44:45], v[70:71], v[6:7] op_sel:[0,1,0]
	v_pk_fma_f32 v[50:51], v[46:47], v[70:71], v[8:9] op_sel:[0,1,0]
	v_add_f32_dpp v12, v12, v12 row_ror:4 row_mask:0xf bank_mask:0xf bound_ctrl:1
	v_add_f32_dpp v136, v136, v136 row_ror:8 row_mask:0xf bank_mask:0xc
	v_add_f32_dpp v136, v128, v128 row_ror:8 row_mask:0xf bank_mask:0x3
	v_add_f32_dpp v12, v12, v12 row_ror:8 row_mask:0xf bank_mask:0xf bound_ctrl:1
	v_pk_fma_f32 v[6:7], v[40:41], v[12:13], v[48:49] op_sel_hi:[1,0,1] neg_lo:[1,0,0] neg_hi:[1,0,0]
	v_pk_fma_f32 v[8:9], v[42:43], v[12:13], v[50:51] op_sel_hi:[1,0,1] neg_lo:[1,0,0] neg_hi:[1,0,0]
	ds_read_b128 v[20:23], v10 offset:41216
	ds_read_b128 v[28:31], v10 offset:41728
	ds_read_b128 v[24:27], v10 offset:41472
	s_waitcnt lgkmcnt(4)
	s_nop 0
	v_fma_mix_f32 v12, v6, v88, v180 op_sel_hi:[0,1,0]
	v_fma_mix_f32 v12, v7, v88, v12 op_sel:[0,1,0] op_sel_hi:[0,1,0]
	v_fma_mix_f32 v12, v8, v89, v12 op_sel_hi:[0,1,0]
	v_fma_mix_f32 v12, v9, v89, v12 op_sel:[0,1,0] op_sel_hi:[0,1,0]
	v_fma_mix_f32 v57, v6, v38, v180 op_sel_hi:[0,1,0]
	v_fma_mix_f32 v57, v7, v38, v57 op_sel:[0,1,0] op_sel_hi:[0,1,0]
	v_add_f32_dpp v12, v12, v12 row_ror:1 row_mask:0xf bank_mask:0xf bound_ctrl:1
	v_fma_mix_f32 v57, v8, v39, v57 op_sel_hi:[0,1,0]
	v_fma_mix_f32 v57, v9, v39, v57 op_sel:[0,1,0] op_sel_hi:[0,1,0]
	v_add_f32_dpp v12, v12, v12 row_ror:2 row_mask:0xf bank_mask:0xf bound_ctrl:1
	v_pk_fma_f32 v[48:49], v[96:97], v[72:73], v[6:7] op_sel_hi:[1,0,1]
	v_pk_fma_f32 v[50:51], v[98:99], v[72:73], v[8:9] op_sel_hi:[1,0,1]
	v_add_f32_dpp v12, v12, v12 row_ror:4 row_mask:0xf bank_mask:0xf bound_ctrl:1
	v_add_f32_dpp v137, v137, v137 row_ror:8 row_mask:0xf bank_mask:0xc
	v_add_f32_dpp v137, v129, v129 row_ror:8 row_mask:0xf bank_mask:0x3
	v_add_f32_dpp v12, v12, v12 row_ror:8 row_mask:0xf bank_mask:0xf bound_ctrl:1
	v_pk_fma_f32 v[6:7], v[92:93], v[12:13], v[48:49] op_sel_hi:[1,0,1] neg_lo:[1,0,0] neg_hi:[1,0,0]
	v_pk_fma_f32 v[8:9], v[94:95], v[12:13], v[50:51] op_sel_hi:[1,0,1] neg_lo:[1,0,0] neg_hi:[1,0,0]
	ds_read_b128 v[36:39], v10 offset:42240
	ds_read_b128 v[44:47], v10 offset:42752
	ds_read_b128 v[40:43], v10 offset:42496
	v_fma_mix_f32 v12, v6, v110, v180 op_sel_hi:[0,1,0]
	v_fma_mix_f32 v12, v7, v110, v12 op_sel:[0,1,0] op_sel_hi:[0,1,0]
	v_fma_mix_f32 v12, v8, v111, v12 op_sel_hi:[0,1,0]
	v_fma_mix_f32 v12, v9, v111, v12 op_sel:[0,1,0] op_sel_hi:[0,1,0]
	v_fma_mix_f32 v81, v6, v90, v180 op_sel_hi:[0,1,0]
	v_fma_mix_f32 v81, v7, v90, v81 op_sel:[0,1,0] op_sel_hi:[0,1,0]
	v_add_f32_dpp v12, v12, v12 row_ror:1 row_mask:0xf bank_mask:0xf bound_ctrl:1
	v_fma_mix_f32 v81, v8, v91, v81 op_sel_hi:[0,1,0]
	v_fma_mix_f32 v81, v9, v91, v81 op_sel:[0,1,0] op_sel_hi:[0,1,0]
	v_add_f32_dpp v12, v12, v12 row_ror:2 row_mask:0xf bank_mask:0xf bound_ctrl:1
	v_pk_fma_f32 v[48:49], v[118:119], v[72:73], v[6:7] op_sel:[0,1,0]
	v_pk_fma_f32 v[50:51], v[120:121], v[72:73], v[8:9] op_sel:[0,1,0]
	v_add_f32_dpp v12, v12, v12 row_ror:4 row_mask:0xf bank_mask:0xf bound_ctrl:1
	v_add_f32_dpp v134, v134, v134 row_ror:4 row_mask:0xf bank_mask:0xa
	v_add_f32_dpp v134, v130, v130 row_ror:12 row_mask:0xf bank_mask:0x5
	v_add_f32_dpp v135, v135, v135 row_ror:4 row_mask:0xf bank_mask:0xa
	v_add_f32_dpp v12, v12, v12 row_ror:8 row_mask:0xf bank_mask:0xf bound_ctrl:1
	v_pk_fma_f32 v[6:7], v[114:115], v[12:13], v[48:49] op_sel_hi:[1,0,1] neg_lo:[1,0,0] neg_hi:[1,0,0]
	v_pk_fma_f32 v[8:9], v[116:117], v[12:13], v[50:51] op_sel_hi:[1,0,1] neg_lo:[1,0,0] neg_hi:[1,0,0]
	v_pk_mul_f32 v[6:7], v[6:7], v[106:107]
	v_pk_mul_f32 v[8:9], v[8:9], v[108:109]
	ds_read_b128 v[88:91], v10 offset:43264
	ds_read_b128 v[96:99], v10 offset:43776
	ds_read_b128 v[92:95], v10 offset:43520
	s_waitcnt lgkmcnt(3)
	s_nop 0
	v_fma_mix_f32 v12, v6, v20, v180 op_sel_hi:[0,1,0]
	v_fma_mix_f32 v12, v7, v20, v12 op_sel:[0,1,0] op_sel_hi:[0,1,0]
	v_fma_mix_f32 v12, v8, v21, v12 op_sel_hi:[0,1,0]
	v_fma_mix_f32 v12, v9, v21, v12 op_sel:[0,1,0] op_sel_hi:[0,1,0]
	v_fma_mix_f32 v82, v6, v112, v180 op_sel_hi:[0,1,0]
	v_fma_mix_f32 v82, v7, v112, v82 op_sel:[0,1,0] op_sel_hi:[0,1,0]
	v_add_f32_dpp v12, v12, v12 row_ror:1 row_mask:0xf bank_mask:0xf bound_ctrl:1
	v_fma_mix_f32 v82, v8, v113, v82 op_sel_hi:[0,1,0]
	v_fma_mix_f32 v82, v9, v113, v82 op_sel:[0,1,0] op_sel_hi:[0,1,0]
	v_add_f32_dpp v12, v12, v12 row_ror:2 row_mask:0xf bank_mask:0xf bound_ctrl:1
	v_pk_fma_f32 v[48:49], v[28:29], v[66:67], v[6:7] op_sel_hi:[1,0,1]
	v_pk_fma_f32 v[50:51], v[30:31], v[66:67], v[8:9] op_sel_hi:[1,0,1]
	v_add_f32_dpp v12, v12, v12 row_ror:4 row_mask:0xf bank_mask:0xf bound_ctrl:1
	v_add_f32_dpp v135, v131, v131 row_ror:12 row_mask:0xf bank_mask:0x5
	v_add_f32_dpp v136, v136, v136 row_ror:4 row_mask:0xf bank_mask:0xa
	v_add_f32_dpp v136, v132, v132 row_ror:12 row_mask:0xf bank_mask:0x5
	v_add_f32_dpp v12, v12, v12 row_ror:8 row_mask:0xf bank_mask:0xf bound_ctrl:1
	v_pk_fma_f32 v[6:7], v[24:25], v[12:13], v[48:49] op_sel_hi:[1,0,1] neg_lo:[1,0,0] neg_hi:[1,0,0]
	v_pk_fma_f32 v[8:9], v[26:27], v[12:13], v[50:51] op_sel_hi:[1,0,1] neg_lo:[1,0,0] neg_hi:[1,0,0]
	ds_read_b128 v[110:113], v10 offset:44288
	ds_read_b128 v[106:109], v10 offset:44032
	ds_read_b128 v[118:121], v10 offset:44800
	ds_read_b128 v[114:117], v10 offset:44544
	ds_read_b128 v[70:73], v11 offset:2816
	v_fma_mix_f32 v12, v6, v36, v180 op_sel_hi:[0,1,0]
	v_fma_mix_f32 v12, v7, v36, v12 op_sel:[0,1,0] op_sel_hi:[0,1,0]
	v_fma_mix_f32 v12, v8, v37, v12 op_sel_hi:[0,1,0]
	v_fma_mix_f32 v12, v9, v37, v12 op_sel:[0,1,0] op_sel_hi:[0,1,0]
	v_fma_mix_f32 v83, v6, v22, v180 op_sel_hi:[0,1,0]
	v_fma_mix_f32 v83, v7, v22, v83 op_sel:[0,1,0] op_sel_hi:[0,1,0]
	v_add_f32_dpp v12, v12, v12 row_ror:1 row_mask:0xf bank_mask:0xf bound_ctrl:1
	v_fma_mix_f32 v83, v8, v23, v83 op_sel_hi:[0,1,0]
	v_fma_mix_f32 v83, v9, v23, v83 op_sel:[0,1,0] op_sel_hi:[0,1,0]
	v_add_f32_dpp v12, v12, v12 row_ror:2 row_mask:0xf bank_mask:0xf bound_ctrl:1
	v_pk_fma_f32 v[48:49], v[44:45], v[66:67], v[6:7] op_sel:[0,1,0]
	v_pk_fma_f32 v[50:51], v[46:47], v[66:67], v[8:9] op_sel:[0,1,0]
	v_add_f32_dpp v12, v12, v12 row_ror:4 row_mask:0xf bank_mask:0xf bound_ctrl:1
	v_add_f32_dpp v137, v137, v137 row_ror:4 row_mask:0xf bank_mask:0xa
	v_add_f32_dpp v137, v133, v133 row_ror:12 row_mask:0xf bank_mask:0x5
	v_add_f32_dpp v12, v12, v12 row_ror:8 row_mask:0xf bank_mask:0xf bound_ctrl:1
	v_pk_fma_f32 v[6:7], v[40:41], v[12:13], v[48:49] op_sel_hi:[1,0,1] neg_lo:[1,0,0] neg_hi:[1,0,0]
	v_pk_fma_f32 v[8:9], v[42:43], v[12:13], v[50:51] op_sel_hi:[1,0,1] neg_lo:[1,0,0] neg_hi:[1,0,0]
	ds_read_b128 v[20:23], v10 offset:45312
	ds_read_b128 v[28:31], v10 offset:45824
	ds_read_b128 v[24:27], v10 offset:45568
	s_waitcnt lgkmcnt(4)
	s_nop 0
	v_fma_mix_f32 v12, v6, v88, v180 op_sel_hi:[0,1,0]
	v_fma_mix_f32 v12, v7, v88, v12 op_sel:[0,1,0] op_sel_hi:[0,1,0]
	v_fma_mix_f32 v12, v8, v89, v12 op_sel_hi:[0,1,0]
	v_fma_mix_f32 v12, v9, v89, v12 op_sel:[0,1,0] op_sel_hi:[0,1,0]
	v_fma_mix_f32 v100, v6, v38, v180 op_sel_hi:[0,1,0]
	v_fma_mix_f32 v100, v7, v38, v100 op_sel:[0,1,0] op_sel_hi:[0,1,0]
	v_add_f32_dpp v12, v12, v12 row_ror:1 row_mask:0xf bank_mask:0xf bound_ctrl:1
	v_fma_mix_f32 v100, v8, v39, v100 op_sel_hi:[0,1,0]
	v_fma_mix_f32 v100, v9, v39, v100 op_sel:[0,1,0] op_sel_hi:[0,1,0]
	v_add_f32_dpp v12, v12, v12 row_ror:2 row_mask:0xf bank_mask:0xf bound_ctrl:1
	v_pk_fma_f32 v[48:49], v[96:97], v[68:69], v[6:7] op_sel_hi:[1,0,1]
	v_pk_fma_f32 v[50:51], v[98:99], v[68:69], v[8:9] op_sel_hi:[1,0,1]
	v_add_f32_dpp v12, v12, v12 row_ror:4 row_mask:0xf bank_mask:0xf bound_ctrl:1
	v_cndmask_b32_e64 v62, v136, v134, s[38:39]
	v_cndmask_b32_e64 v63, v134, v136, s[38:39]
	v_add_f32_dpp v12, v12, v12 row_ror:8 row_mask:0xf bank_mask:0xf bound_ctrl:1
	v_pk_fma_f32 v[6:7], v[92:93], v[12:13], v[48:49] op_sel_hi:[1,0,1] neg_lo:[1,0,0] neg_hi:[1,0,0]
	v_pk_fma_f32 v[8:9], v[94:95], v[12:13], v[50:51] op_sel_hi:[1,0,1] neg_lo:[1,0,0] neg_hi:[1,0,0]
	ds_read_b128 v[36:39], v10 offset:46336
	ds_read_b128 v[44:47], v10 offset:46848
	ds_read_b128 v[40:43], v10 offset:46592
	v_fma_mix_f32 v12, v6, v110, v180 op_sel_hi:[0,1,0]
	v_fma_mix_f32 v12, v7, v110, v12 op_sel:[0,1,0] op_sel_hi:[0,1,0]
	v_fma_mix_f32 v12, v8, v111, v12 op_sel_hi:[0,1,0]
	v_fma_mix_f32 v12, v9, v111, v12 op_sel:[0,1,0] op_sel_hi:[0,1,0]
	v_fma_mix_f32 v101, v6, v90, v180 op_sel_hi:[0,1,0]
	v_fma_mix_f32 v101, v7, v90, v101 op_sel:[0,1,0] op_sel_hi:[0,1,0]
	v_add_f32_dpp v12, v12, v12 row_ror:1 row_mask:0xf bank_mask:0xf bound_ctrl:1
	v_fma_mix_f32 v101, v8, v91, v101 op_sel_hi:[0,1,0]
	v_fma_mix_f32 v101, v9, v91, v101 op_sel:[0,1,0] op_sel_hi:[0,1,0]
	v_add_f32_dpp v12, v12, v12 row_ror:2 row_mask:0xf bank_mask:0xf bound_ctrl:1
	v_pk_fma_f32 v[48:49], v[118:119], v[68:69], v[6:7] op_sel:[0,1,0]
	v_pk_fma_f32 v[50:51], v[120:121], v[68:69], v[8:9] op_sel:[0,1,0]
	v_add_f32_dpp v12, v12, v12 row_ror:4 row_mask:0xf bank_mask:0xf bound_ctrl:1
	v_cndmask_b32_e64 v64, v137, v135, s[38:39]
	v_cndmask_b32_e64 v65, v135, v137, s[38:39]
	v_add_f32_dpp v12, v12, v12 row_ror:8 row_mask:0xf bank_mask:0xf bound_ctrl:1
	v_pk_fma_f32 v[6:7], v[114:115], v[12:13], v[48:49] op_sel_hi:[1,0,1] neg_lo:[1,0,0] neg_hi:[1,0,0]
	v_pk_fma_f32 v[8:9], v[116:117], v[12:13], v[50:51] op_sel_hi:[1,0,1] neg_lo:[1,0,0] neg_hi:[1,0,0]
	v_pk_mul_f32 v[6:7], v[6:7], v[106:107]
	v_pk_mul_f32 v[8:9], v[8:9], v[108:109]
	ds_read_b128 v[88:91], v10 offset:47360
	ds_read_b128 v[96:99], v10 offset:47872
	ds_read_b128 v[92:95], v10 offset:47616
	s_waitcnt lgkmcnt(3)
	s_nop 0
	v_fma_mix_f32 v12, v6, v20, v180 op_sel_hi:[0,1,0]
	v_fma_mix_f32 v12, v7, v20, v12 op_sel:[0,1,0] op_sel_hi:[0,1,0]
	v_fma_mix_f32 v12, v8, v21, v12 op_sel_hi:[0,1,0]
	v_fma_mix_f32 v12, v9, v21, v12 op_sel:[0,1,0] op_sel_hi:[0,1,0]
	v_fma_mix_f32 v102, v6, v112, v180 op_sel_hi:[0,1,0]
	v_fma_mix_f32 v102, v7, v112, v102 op_sel:[0,1,0] op_sel_hi:[0,1,0]
	v_add_f32_dpp v12, v12, v12 row_ror:1 row_mask:0xf bank_mask:0xf bound_ctrl:1
	v_fma_mix_f32 v102, v8, v113, v102 op_sel_hi:[0,1,0]
	v_fma_mix_f32 v102, v9, v113, v102 op_sel:[0,1,0] op_sel_hi:[0,1,0]
	v_add_f32_dpp v12, v12, v12 row_ror:2 row_mask:0xf bank_mask:0xf bound_ctrl:1
	v_pk_fma_f32 v[48:49], v[28:29], v[70:71], v[6:7] op_sel_hi:[1,0,1]
	v_pk_fma_f32 v[50:51], v[30:31], v[70:71], v[8:9] op_sel_hi:[1,0,1]
	v_add_f32_dpp v12, v12, v12 row_ror:4 row_mask:0xf bank_mask:0xf bound_ctrl:1
	v_add_f32_dpp v62, v63, v62 quad_perm:[2,3,0,1] row_mask:0xf bank_mask:0xf bound_ctrl:1
	v_add_f32_dpp v63, v65, v64 quad_perm:[2,3,0,1] row_mask:0xf bank_mask:0xf bound_ctrl:1
	v_add_f32_dpp v12, v12, v12 row_ror:8 row_mask:0xf bank_mask:0xf bound_ctrl:1
	v_pk_fma_f32 v[6:7], v[24:25], v[12:13], v[48:49] op_sel_hi:[1,0,1] neg_lo:[1,0,0] neg_hi:[1,0,0]
	v_pk_fma_f32 v[8:9], v[26:27], v[12:13], v[50:51] op_sel_hi:[1,0,1] neg_lo:[1,0,0] neg_hi:[1,0,0]
	ds_read_b128 v[110:113], v10 offset:48384
	ds_read_b128 v[106:109], v10 offset:48128
	ds_read_b128 v[118:121], v10 offset:48896
	ds_read_b128 v[114:117], v10 offset:48640
	ds_read_b128 v[66:69], v11 offset:3072
	v_fma_mix_f32 v12, v6, v36, v180 op_sel_hi:[0,1,0]
	v_fma_mix_f32 v12, v7, v36, v12 op_sel:[0,1,0] op_sel_hi:[0,1,0]
	v_fma_mix_f32 v12, v8, v37, v12 op_sel_hi:[0,1,0]
	v_fma_mix_f32 v12, v9, v37, v12 op_sel:[0,1,0] op_sel_hi:[0,1,0]
	v_fma_mix_f32 v103, v6, v22, v180 op_sel_hi:[0,1,0]
	v_fma_mix_f32 v103, v7, v22, v103 op_sel:[0,1,0] op_sel_hi:[0,1,0]
	v_add_f32_dpp v12, v12, v12 row_ror:1 row_mask:0xf bank_mask:0xf bound_ctrl:1
	v_fma_mix_f32 v103, v8, v23, v103 op_sel_hi:[0,1,0]
	v_fma_mix_f32 v103, v9, v23, v103 op_sel:[0,1,0] op_sel_hi:[0,1,0]
	v_add_f32_dpp v12, v12, v12 row_ror:2 row_mask:0xf bank_mask:0xf bound_ctrl:1
	v_pk_fma_f32 v[48:49], v[44:45], v[70:71], v[6:7] op_sel:[0,1,0]
	v_pk_fma_f32 v[50:51], v[46:47], v[70:71], v[8:9] op_sel:[0,1,0]
	v_add_f32_dpp v12, v12, v12 row_ror:4 row_mask:0xf bank_mask:0xf bound_ctrl:1
	v_cndmask_b32_e64 v65, v63, v62, s[40:41]
	v_cndmask_b32_e64 v62, v62, v63, s[40:41]
	v_add_f32_dpp v12, v12, v12 row_ror:8 row_mask:0xf bank_mask:0xf bound_ctrl:1
	v_pk_fma_f32 v[6:7], v[40:41], v[12:13], v[48:49] op_sel_hi:[1,0,1] neg_lo:[1,0,0] neg_hi:[1,0,0]
	v_pk_fma_f32 v[8:9], v[42:43], v[12:13], v[50:51] op_sel_hi:[1,0,1] neg_lo:[1,0,0] neg_hi:[1,0,0]
	ds_read_b128 v[20:23], v10 offset:49408
	ds_read_b128 v[28:31], v10 offset:49920
	ds_read_b128 v[24:27], v10 offset:49664
	s_waitcnt lgkmcnt(4)
	s_nop 0
	v_fma_mix_f32 v12, v6, v88, v180 op_sel_hi:[0,1,0]
	v_fma_mix_f32 v12, v7, v88, v12 op_sel:[0,1,0] op_sel_hi:[0,1,0]
	v_fma_mix_f32 v12, v8, v89, v12 op_sel_hi:[0,1,0]
	v_fma_mix_f32 v12, v9, v89, v12 op_sel:[0,1,0] op_sel_hi:[0,1,0]
	v_fma_mix_f32 v104, v6, v38, v180 op_sel_hi:[0,1,0]
	v_fma_mix_f32 v104, v7, v38, v104 op_sel:[0,1,0] op_sel_hi:[0,1,0]
	v_add_f32_dpp v12, v12, v12 row_ror:1 row_mask:0xf bank_mask:0xf bound_ctrl:1
	v_fma_mix_f32 v104, v8, v39, v104 op_sel_hi:[0,1,0]
	v_fma_mix_f32 v104, v9, v39, v104 op_sel:[0,1,0] op_sel_hi:[0,1,0]
	v_add_f32_dpp v12, v12, v12 row_ror:2 row_mask:0xf bank_mask:0xf bound_ctrl:1
	v_pk_fma_f32 v[48:49], v[96:97], v[72:73], v[6:7] op_sel_hi:[1,0,1]
	v_pk_fma_f32 v[50:51], v[98:99], v[72:73], v[8:9] op_sel_hi:[1,0,1]
	v_add_f32_dpp v12, v12, v12 row_ror:4 row_mask:0xf bank_mask:0xf bound_ctrl:1
	v_add_f32_dpp v62, v62, v65 quad_perm:[1,0,3,2] row_mask:0xf bank_mask:0xf bound_ctrl:1
	v_cvt_pk_bf16_f32 v62, v62, v62
	v_add_f32_dpp v12, v12, v12 row_ror:8 row_mask:0xf bank_mask:0xf bound_ctrl:1
	v_pk_fma_f32 v[6:7], v[92:93], v[12:13], v[48:49] op_sel_hi:[1,0,1] neg_lo:[1,0,0] neg_hi:[1,0,0]
	v_pk_fma_f32 v[8:9], v[94:95], v[12:13], v[50:51] op_sel_hi:[1,0,1] neg_lo:[1,0,0] neg_hi:[1,0,0]
	ds_read_b128 v[36:39], v10 offset:50432
	ds_read_b128 v[44:47], v10 offset:50944
	ds_read_b128 v[40:43], v10 offset:50688
	v_fma_mix_f32 v12, v6, v110, v180 op_sel_hi:[0,1,0]
	v_fma_mix_f32 v12, v7, v110, v12 op_sel:[0,1,0] op_sel_hi:[0,1,0]
	v_fma_mix_f32 v12, v8, v111, v12 op_sel_hi:[0,1,0]
	v_fma_mix_f32 v12, v9, v111, v12 op_sel:[0,1,0] op_sel_hi:[0,1,0]
	v_fma_mix_f32 v105, v6, v90, v180 op_sel_hi:[0,1,0]
	v_fma_mix_f32 v105, v7, v90, v105 op_sel:[0,1,0] op_sel_hi:[0,1,0]
	v_add_f32_dpp v12, v12, v12 row_ror:1 row_mask:0xf bank_mask:0xf bound_ctrl:1
	v_fma_mix_f32 v105, v8, v91, v105 op_sel_hi:[0,1,0]
	v_fma_mix_f32 v105, v9, v91, v105 op_sel:[0,1,0] op_sel_hi:[0,1,0]
	v_add_f32_dpp v12, v12, v12 row_ror:2 row_mask:0xf bank_mask:0xf bound_ctrl:1
	v_pk_fma_f32 v[48:49], v[118:119], v[72:73], v[6:7] op_sel:[0,1,0]
	v_pk_fma_f32 v[50:51], v[120:121], v[72:73], v[8:9] op_sel:[0,1,0]
	v_add_f32_dpp v12, v12, v12 row_ror:4 row_mask:0xf bank_mask:0xf bound_ctrl:1
	global_store_short v[2:3], v62, off
	v_lshl_add_u64 v[2:3], v[2:3], 0, s[84:85]
	v_add_f32_dpp v12, v12, v12 row_ror:8 row_mask:0xf bank_mask:0xf bound_ctrl:1
	v_pk_fma_f32 v[6:7], v[114:115], v[12:13], v[48:49] op_sel_hi:[1,0,1] neg_lo:[1,0,0] neg_hi:[1,0,0]
	v_pk_fma_f32 v[8:9], v[116:117], v[12:13], v[50:51] op_sel_hi:[1,0,1] neg_lo:[1,0,0] neg_hi:[1,0,0]
	v_pk_mul_f32 v[6:7], v[6:7], v[106:107]
	v_pk_mul_f32 v[8:9], v[8:9], v[108:109]
	ds_read_b128 v[88:91], v10 offset:51456
	ds_read_b128 v[96:99], v10 offset:51968
	ds_read_b128 v[92:95], v10 offset:51712
	s_waitcnt lgkmcnt(3)
	s_nop 0
	v_fma_mix_f32 v12, v6, v20, v180 op_sel_hi:[0,1,0]
	v_fma_mix_f32 v12, v7, v20, v12 op_sel:[0,1,0] op_sel_hi:[0,1,0]
	v_fma_mix_f32 v12, v8, v21, v12 op_sel_hi:[0,1,0]
	v_fma_mix_f32 v12, v9, v21, v12 op_sel:[0,1,0] op_sel_hi:[0,1,0]
	v_fma_mix_f32 v61, v6, v112, v180 op_sel_hi:[0,1,0]
	v_fma_mix_f32 v61, v7, v112, v61 op_sel:[0,1,0] op_sel_hi:[0,1,0]
	v_add_f32_dpp v12, v12, v12 row_ror:1 row_mask:0xf bank_mask:0xf bound_ctrl:1
	v_fma_mix_f32 v61, v8, v113, v61 op_sel_hi:[0,1,0]
	v_fma_mix_f32 v61, v9, v113, v61 op_sel:[0,1,0] op_sel_hi:[0,1,0]
	v_add_f32_dpp v12, v12, v12 row_ror:2 row_mask:0xf bank_mask:0xf bound_ctrl:1
	v_pk_fma_f32 v[48:49], v[28:29], v[66:67], v[6:7] op_sel_hi:[1,0,1]
	v_pk_fma_f32 v[50:51], v[30:31], v[66:67], v[8:9] op_sel_hi:[1,0,1]
	v_add_f32_dpp v12, v12, v12 row_ror:4 row_mask:0xf bank_mask:0xf bound_ctrl:1
	s_nop 1
	s_nop 0
	v_add_f32_dpp v12, v12, v12 row_ror:8 row_mask:0xf bank_mask:0xf bound_ctrl:1
	v_pk_fma_f32 v[6:7], v[24:25], v[12:13], v[48:49] op_sel_hi:[1,0,1] neg_lo:[1,0,0] neg_hi:[1,0,0]
	v_pk_fma_f32 v[8:9], v[26:27], v[12:13], v[50:51] op_sel_hi:[1,0,1] neg_lo:[1,0,0] neg_hi:[1,0,0]
	ds_read_b128 v[110:113], v10 offset:52480
	ds_read_b128 v[106:109], v10 offset:52224
	ds_read_b128 v[118:121], v10 offset:52992
	ds_read_b128 v[114:117], v10 offset:52736
	ds_read_b128 v[70:73], v11 offset:3328
	v_fma_mix_f32 v12, v6, v36, v180 op_sel_hi:[0,1,0]
	v_fma_mix_f32 v12, v7, v36, v12 op_sel:[0,1,0] op_sel_hi:[0,1,0]
	v_fma_mix_f32 v12, v8, v37, v12 op_sel_hi:[0,1,0]
	v_fma_mix_f32 v12, v9, v37, v12 op_sel:[0,1,0] op_sel_hi:[0,1,0]
	v_fma_mix_f32 v122, v6, v22, v180 op_sel_hi:[0,1,0]
	v_fma_mix_f32 v122, v7, v22, v122 op_sel:[0,1,0] op_sel_hi:[0,1,0]
	v_add_f32_dpp v12, v12, v12 row_ror:1 row_mask:0xf bank_mask:0xf bound_ctrl:1
	v_fma_mix_f32 v122, v8, v23, v122 op_sel_hi:[0,1,0]
	v_fma_mix_f32 v122, v9, v23, v122 op_sel:[0,1,0] op_sel_hi:[0,1,0]
	v_add_f32_dpp v12, v12, v12 row_ror:2 row_mask:0xf bank_mask:0xf bound_ctrl:1
	v_pk_fma_f32 v[48:49], v[44:45], v[66:67], v[6:7] op_sel:[0,1,0]
	v_pk_fma_f32 v[50:51], v[46:47], v[66:67], v[8:9] op_sel:[0,1,0]
	v_add_f32_dpp v12, v12, v12 row_ror:4 row_mask:0xf bank_mask:0xf bound_ctrl:1
	v_add_f32_dpp v83, v83, v83 row_ror:8 row_mask:0xf bank_mask:0xc
	v_add_f32_dpp v83, v52, v52 row_ror:8 row_mask:0xf bank_mask:0x3
	v_add_f32_dpp v100, v100, v100 row_ror:8 row_mask:0xf bank_mask:0xc
	v_add_f32_dpp v12, v12, v12 row_ror:8 row_mask:0xf bank_mask:0xf bound_ctrl:1
	v_pk_fma_f32 v[6:7], v[40:41], v[12:13], v[48:49] op_sel_hi:[1,0,1] neg_lo:[1,0,0] neg_hi:[1,0,0]
	v_pk_fma_f32 v[8:9], v[42:43], v[12:13], v[50:51] op_sel_hi:[1,0,1] neg_lo:[1,0,0] neg_hi:[1,0,0]
	ds_read_b128 v[20:23], v10 offset:53504
	ds_read_b128 v[28:31], v10 offset:54016
	ds_read_b128 v[24:27], v10 offset:53760
	s_waitcnt lgkmcnt(4)
	s_nop 0
	v_fma_mix_f32 v12, v6, v88, v180 op_sel_hi:[0,1,0]
	v_fma_mix_f32 v12, v7, v88, v12 op_sel:[0,1,0] op_sel_hi:[0,1,0]
	v_fma_mix_f32 v12, v8, v89, v12 op_sel_hi:[0,1,0]
	v_fma_mix_f32 v12, v9, v89, v12 op_sel:[0,1,0] op_sel_hi:[0,1,0]
	v_fma_mix_f32 v123, v6, v38, v180 op_sel_hi:[0,1,0]
	v_fma_mix_f32 v123, v7, v38, v123 op_sel:[0,1,0] op_sel_hi:[0,1,0]
	v_add_f32_dpp v12, v12, v12 row_ror:1 row_mask:0xf bank_mask:0xf bound_ctrl:1
	v_fma_mix_f32 v123, v8, v39, v123 op_sel_hi:[0,1,0]
	v_fma_mix_f32 v123, v9, v39, v123 op_sel:[0,1,0] op_sel_hi:[0,1,0]
	v_add_f32_dpp v12, v12, v12 row_ror:2 row_mask:0xf bank_mask:0xf bound_ctrl:1
	v_pk_fma_f32 v[48:49], v[96:97], v[68:69], v[6:7] op_sel_hi:[1,0,1]
	v_pk_fma_f32 v[50:51], v[98:99], v[68:69], v[8:9] op_sel_hi:[1,0,1]
	v_add_f32_dpp v12, v12, v12 row_ror:4 row_mask:0xf bank_mask:0xf bound_ctrl:1
	v_add_f32_dpp v100, v53, v53 row_ror:8 row_mask:0xf bank_mask:0x3
	v_add_f32_dpp v101, v101, v101 row_ror:8 row_mask:0xf bank_mask:0xc
	v_add_f32_dpp v101, v54, v54 row_ror:8 row_mask:0xf bank_mask:0x3
	v_add_f32_dpp v12, v12, v12 row_ror:8 row_mask:0xf bank_mask:0xf bound_ctrl:1
	v_pk_fma_f32 v[6:7], v[92:93], v[12:13], v[48:49] op_sel_hi:[1,0,1] neg_lo:[1,0,0] neg_hi:[1,0,0]
	v_pk_fma_f32 v[8:9], v[94:95], v[12:13], v[50:51] op_sel_hi:[1,0,1] neg_lo:[1,0,0] neg_hi:[1,0,0]
	ds_read_b128 v[36:39], v10 offset:54528
	ds_read_b128 v[44:47], v10 offset:55040
	ds_read_b128 v[40:43], v10 offset:54784
	v_fma_mix_f32 v12, v6, v110, v180 op_sel_hi:[0,1,0]
	v_fma_mix_f32 v12, v7, v110, v12 op_sel:[0,1,0] op_sel_hi:[0,1,0]
	v_fma_mix_f32 v12, v8, v111, v12 op_sel_hi:[0,1,0]
	v_fma_mix_f32 v12, v9, v111, v12 op_sel:[0,1,0] op_sel_hi:[0,1,0]
	v_fma_mix_f32 v124, v6, v90, v180 op_sel_hi:[0,1,0]
	v_fma_mix_f32 v124, v7, v90, v124 op_sel:[0,1,0] op_sel_hi:[0,1,0]
	v_add_f32_dpp v12, v12, v12 row_ror:1 row_mask:0xf bank_mask:0xf bound_ctrl:1
	v_fma_mix_f32 v124, v8, v91, v124 op_sel_hi:[0,1,0]
	v_fma_mix_f32 v124, v9, v91, v124 op_sel:[0,1,0] op_sel_hi:[0,1,0]
	v_add_f32_dpp v12, v12, v12 row_ror:2 row_mask:0xf bank_mask:0xf bound_ctrl:1
	v_pk_fma_f32 v[48:49], v[118:119], v[68:69], v[6:7] op_sel:[0,1,0]
	v_pk_fma_f32 v[50:51], v[120:121], v[68:69], v[8:9] op_sel:[0,1,0]
	v_add_f32_dpp v12, v12, v12 row_ror:4 row_mask:0xf bank_mask:0xf bound_ctrl:1
	v_add_f32_dpp v102, v102, v102 row_ror:8 row_mask:0xf bank_mask:0xc
	v_add_f32_dpp v102, v55, v55 row_ror:8 row_mask:0xf bank_mask:0x3
	v_add_f32_dpp v103, v103, v103 row_ror:8 row_mask:0xf bank_mask:0xc
	v_add_f32_dpp v12, v12, v12 row_ror:8 row_mask:0xf bank_mask:0xf bound_ctrl:1
	v_pk_fma_f32 v[6:7], v[114:115], v[12:13], v[48:49] op_sel_hi:[1,0,1] neg_lo:[1,0,0] neg_hi:[1,0,0]
	v_pk_fma_f32 v[8:9], v[116:117], v[12:13], v[50:51] op_sel_hi:[1,0,1] neg_lo:[1,0,0] neg_hi:[1,0,0]
	v_pk_mul_f32 v[6:7], v[6:7], v[106:107]
	v_pk_mul_f32 v[8:9], v[8:9], v[108:109]
	ds_read_b128 v[88:91], v10 offset:55552
	ds_read_b128 v[96:99], v10 offset:56064
	ds_read_b128 v[92:95], v10 offset:55808
	s_waitcnt lgkmcnt(3)
	s_nop 0
	v_fma_mix_f32 v12, v6, v20, v180 op_sel_hi:[0,1,0]
	v_fma_mix_f32 v12, v7, v20, v12 op_sel:[0,1,0] op_sel_hi:[0,1,0]
	v_fma_mix_f32 v12, v8, v21, v12 op_sel_hi:[0,1,0]
	v_fma_mix_f32 v12, v9, v21, v12 op_sel:[0,1,0] op_sel_hi:[0,1,0]
	v_fma_mix_f32 v125, v6, v112, v180 op_sel_hi:[0,1,0]
	v_fma_mix_f32 v125, v7, v112, v125 op_sel:[0,1,0] op_sel_hi:[0,1,0]
	v_add_f32_dpp v12, v12, v12 row_ror:1 row_mask:0xf bank_mask:0xf bound_ctrl:1
	v_fma_mix_f32 v125, v8, v113, v125 op_sel_hi:[0,1,0]
	v_fma_mix_f32 v125, v9, v113, v125 op_sel:[0,1,0] op_sel_hi:[0,1,0]
	v_add_f32_dpp v12, v12, v12 row_ror:2 row_mask:0xf bank_mask:0xf bound_ctrl:1
	v_pk_fma_f32 v[48:49], v[28:29], v[70:71], v[6:7] op_sel_hi:[1,0,1]
	v_pk_fma_f32 v[50:51], v[30:31], v[70:71], v[8:9] op_sel_hi:[1,0,1]
	v_add_f32_dpp v12, v12, v12 row_ror:4 row_mask:0xf bank_mask:0xf bound_ctrl:1
	v_add_f32_dpp v103, v56, v56 row_ror:8 row_mask:0xf bank_mask:0x3
	v_add_f32_dpp v104, v104, v104 row_ror:8 row_mask:0xf bank_mask:0xc
	v_add_f32_dpp v104, v57, v57 row_ror:8 row_mask:0xf bank_mask:0x3
	v_add_f32_dpp v12, v12, v12 row_ror:8 row_mask:0xf bank_mask:0xf bound_ctrl:1
	v_pk_fma_f32 v[6:7], v[24:25], v[12:13], v[48:49] op_sel_hi:[1,0,1] neg_lo:[1,0,0] neg_hi:[1,0,0]
	v_pk_fma_f32 v[8:9], v[26:27], v[12:13], v[50:51] op_sel_hi:[1,0,1] neg_lo:[1,0,0] neg_hi:[1,0,0]
	ds_read_b128 v[110:113], v10 offset:56576
	ds_read_b128 v[106:109], v10 offset:56320
	ds_read_b128 v[118:121], v10 offset:57088
	ds_read_b128 v[114:117], v10 offset:56832
	ds_read_b128 v[66:69], v11 offset:3584
	v_fma_mix_f32 v12, v6, v36, v180 op_sel_hi:[0,1,0]
	v_fma_mix_f32 v12, v7, v36, v12 op_sel:[0,1,0] op_sel_hi:[0,1,0]
	v_fma_mix_f32 v12, v8, v37, v12 op_sel_hi:[0,1,0]
	v_fma_mix_f32 v12, v9, v37, v12 op_sel:[0,1,0] op_sel_hi:[0,1,0]
	v_fma_mix_f32 v126, v6, v22, v180 op_sel_hi:[0,1,0]
	v_fma_mix_f32 v126, v7, v22, v126 op_sel:[0,1,0] op_sel_hi:[0,1,0]
	v_add_f32_dpp v12, v12, v12 row_ror:1 row_mask:0xf bank_mask:0xf bound_ctrl:1
	v_fma_mix_f32 v126, v8, v23, v126 op_sel_hi:[0,1,0]
	v_fma_mix_f32 v126, v9, v23, v126 op_sel:[0,1,0] op_sel_hi:[0,1,0]
	v_add_f32_dpp v12, v12, v12 row_ror:2 row_mask:0xf bank_mask:0xf bound_ctrl:1
	v_pk_fma_f32 v[48:49], v[44:45], v[70:71], v[6:7] op_sel:[0,1,0]
	v_pk_fma_f32 v[50:51], v[46:47], v[70:71], v[8:9] op_sel:[0,1,0]
	v_add_f32_dpp v12, v12, v12 row_ror:4 row_mask:0xf bank_mask:0xf bound_ctrl:1
	v_add_f32_dpp v105, v105, v105 row_ror:8 row_mask:0xf bank_mask:0xc
	v_add_f32_dpp v105, v81, v81 row_ror:8 row_mask:0xf bank_mask:0x3
	v_add_f32_dpp v12, v12, v12 row_ror:8 row_mask:0xf bank_mask:0xf bound_ctrl:1
	v_pk_fma_f32 v[6:7], v[40:41], v[12:13], v[48:49] op_sel_hi:[1,0,1] neg_lo:[1,0,0] neg_hi:[1,0,0]
	v_pk_fma_f32 v[8:9], v[42:43], v[12:13], v[50:51] op_sel_hi:[1,0,1] neg_lo:[1,0,0] neg_hi:[1,0,0]
	ds_read_b128 v[20:23], v10 offset:57600
	ds_read_b128 v[28:31], v10 offset:58112
	ds_read_b128 v[24:27], v10 offset:57856
	s_waitcnt lgkmcnt(4)
	s_nop 0
	v_fma_mix_f32 v12, v6, v88, v180 op_sel_hi:[0,1,0]
	v_fma_mix_f32 v12, v7, v88, v12 op_sel:[0,1,0] op_sel_hi:[0,1,0]
	v_fma_mix_f32 v12, v8, v89, v12 op_sel_hi:[0,1,0]
	v_fma_mix_f32 v12, v9, v89, v12 op_sel:[0,1,0] op_sel_hi:[0,1,0]
	v_fma_mix_f32 v127, v6, v38, v180 op_sel_hi:[0,1,0]
	v_fma_mix_f32 v127, v7, v38, v127 op_sel:[0,1,0] op_sel_hi:[0,1,0]
	v_add_f32_dpp v12, v12, v12 row_ror:1 row_mask:0xf bank_mask:0xf bound_ctrl:1
	v_fma_mix_f32 v127, v8, v39, v127 op_sel_hi:[0,1,0]
	v_fma_mix_f32 v127, v9, v39, v127 op_sel:[0,1,0] op_sel_hi:[0,1,0]
	v_add_f32_dpp v12, v12, v12 row_ror:2 row_mask:0xf bank_mask:0xf bound_ctrl:1
	v_pk_fma_f32 v[48:49], v[96:97], v[72:73], v[6:7] op_sel_hi:[1,0,1]
	v_pk_fma_f32 v[50:51], v[98:99], v[72:73], v[8:9] op_sel_hi:[1,0,1]
	v_add_f32_dpp v12, v12, v12 row_ror:4 row_mask:0xf bank_mask:0xf bound_ctrl:1
	v_add_f32_dpp v61, v61, v61 row_ror:8 row_mask:0xf bank_mask:0xc
	v_add_f32_dpp v61, v82, v82 row_ror:8 row_mask:0xf bank_mask:0x3
	v_add_f32_dpp v12, v12, v12 row_ror:8 row_mask:0xf bank_mask:0xf bound_ctrl:1
	v_pk_fma_f32 v[6:7], v[92:93], v[12:13], v[48:49] op_sel_hi:[1,0,1] neg_lo:[1,0,0] neg_hi:[1,0,0]
	v_pk_fma_f32 v[8:9], v[94:95], v[12:13], v[50:51] op_sel_hi:[1,0,1] neg_lo:[1,0,0] neg_hi:[1,0,0]
	ds_read_b128 v[36:39], v10 offset:58624
	ds_read_b128 v[44:47], v10 offset:59136
	ds_read_b128 v[40:43], v10 offset:58880
	v_fma_mix_f32 v12, v6, v110, v180 op_sel_hi:[0,1,0]
	v_fma_mix_f32 v12, v7, v110, v12 op_sel:[0,1,0] op_sel_hi:[0,1,0]
	v_fma_mix_f32 v12, v8, v111, v12 op_sel_hi:[0,1,0]
	v_fma_mix_f32 v12, v9, v111, v12 op_sel:[0,1,0] op_sel_hi:[0,1,0]
	v_fma_mix_f32 v128, v6, v90, v180 op_sel_hi:[0,1,0]
	v_fma_mix_f32 v128, v7, v90, v128 op_sel:[0,1,0] op_sel_hi:[0,1,0]
	v_add_f32_dpp v12, v12, v12 row_ror:1 row_mask:0xf bank_mask:0xf bound_ctrl:1
	v_fma_mix_f32 v128, v8, v91, v128 op_sel_hi:[0,1,0]
	v_fma_mix_f32 v128, v9, v91, v128 op_sel:[0,1,0] op_sel_hi:[0,1,0]
	v_add_f32_dpp v12, v12, v12 row_ror:2 row_mask:0xf bank_mask:0xf bound_ctrl:1
	v_pk_fma_f32 v[48:49], v[118:119], v[72:73], v[6:7] op_sel:[0,1,0]
	v_pk_fma_f32 v[50:51], v[120:121], v[72:73], v[8:9] op_sel:[0,1,0]
	v_add_f32_dpp v12, v12, v12 row_ror:4 row_mask:0xf bank_mask:0xf bound_ctrl:1
	v_add_f32_dpp v103, v103, v103 row_ror:4 row_mask:0xf bank_mask:0xa
	v_add_f32_dpp v103, v83, v83 row_ror:12 row_mask:0xf bank_mask:0x5
	v_add_f32_dpp v104, v104, v104 row_ror:4 row_mask:0xf bank_mask:0xa
	v_add_f32_dpp v12, v12, v12 row_ror:8 row_mask:0xf bank_mask:0xf bound_ctrl:1
	v_pk_fma_f32 v[6:7], v[114:115], v[12:13], v[48:49] op_sel_hi:[1,0,1] neg_lo:[1,0,0] neg_hi:[1,0,0]
	v_pk_fma_f32 v[8:9], v[116:117], v[12:13], v[50:51] op_sel_hi:[1,0,1] neg_lo:[1,0,0] neg_hi:[1,0,0]
	v_pk_mul_f32 v[6:7], v[6:7], v[106:107]
	v_pk_mul_f32 v[8:9], v[8:9], v[108:109]
	ds_read_b128 v[88:91], v10 offset:59648
	ds_read_b128 v[96:99], v10 offset:60160
	ds_read_b128 v[92:95], v10 offset:59904
	s_waitcnt lgkmcnt(3)
	s_nop 0
	v_fma_mix_f32 v12, v6, v20, v180 op_sel_hi:[0,1,0]
	v_fma_mix_f32 v12, v7, v20, v12 op_sel:[0,1,0] op_sel_hi:[0,1,0]
	v_fma_mix_f32 v12, v8, v21, v12 op_sel_hi:[0,1,0]
	v_fma_mix_f32 v12, v9, v21, v12 op_sel:[0,1,0] op_sel_hi:[0,1,0]
	v_fma_mix_f32 v129, v6, v112, v180 op_sel_hi:[0,1,0]
	v_fma_mix_f32 v129, v7, v112, v129 op_sel:[0,1,0] op_sel_hi:[0,1,0]
	v_add_f32_dpp v12, v12, v12 row_ror:1 row_mask:0xf bank_mask:0xf bound_ctrl:1
	v_fma_mix_f32 v129, v8, v113, v129 op_sel_hi:[0,1,0]
	v_fma_mix_f32 v129, v9, v113, v129 op_sel:[0,1,0] op_sel_hi:[0,1,0]
	v_add_f32_dpp v12, v12, v12 row_ror:2 row_mask:0xf bank_mask:0xf bound_ctrl:1
	v_pk_fma_f32 v[48:49], v[28:29], v[66:67], v[6:7] op_sel_hi:[1,0,1]
	v_pk_fma_f32 v[50:51], v[30:31], v[66:67], v[8:9] op_sel_hi:[1,0,1]
	v_add_f32_dpp v12, v12, v12 row_ror:4 row_mask:0xf bank_mask:0xf bound_ctrl:1
	v_add_f32_dpp v104, v100, v100 row_ror:12 row_mask:0xf bank_mask:0x5
	v_add_f32_dpp v105, v105, v105 row_ror:4 row_mask:0xf bank_mask:0xa
	v_add_f32_dpp v105, v101, v101 row_ror:12 row_mask:0xf bank_mask:0x5
	v_add_f32_dpp v12, v12, v12 row_ror:8 row_mask:0xf bank_mask:0xf bound_ctrl:1
	v_pk_fma_f32 v[6:7], v[24:25], v[12:13], v[48:49] op_sel_hi:[1,0,1] neg_lo:[1,0,0] neg_hi:[1,0,0]
	v_pk_fma_f32 v[8:9], v[26:27], v[12:13], v[50:51] op_sel_hi:[1,0,1] neg_lo:[1,0,0] neg_hi:[1,0,0]
	ds_read_b128 v[110:113], v10 offset:60672
	ds_read_b128 v[106:109], v10 offset:60416
	ds_read_b128 v[118:121], v10 offset:61184
	ds_read_b128 v[114:117], v10 offset:60928
	ds_read_b128 v[70:73], v11 offset:3840
	v_fma_mix_f32 v12, v6, v36, v180 op_sel_hi:[0,1,0]
	v_fma_mix_f32 v12, v7, v36, v12 op_sel:[0,1,0] op_sel_hi:[0,1,0]
	v_fma_mix_f32 v12, v8, v37, v12 op_sel_hi:[0,1,0]
	v_fma_mix_f32 v12, v9, v37, v12 op_sel:[0,1,0] op_sel_hi:[0,1,0]
	v_fma_mix_f32 v130, v6, v22, v180 op_sel_hi:[0,1,0]
	v_fma_mix_f32 v130, v7, v22, v130 op_sel:[0,1,0] op_sel_hi:[0,1,0]
	v_add_f32_dpp v12, v12, v12 row_ror:1 row_mask:0xf bank_mask:0xf bound_ctrl:1
	v_fma_mix_f32 v130, v8, v23, v130 op_sel_hi:[0,1,0]
	v_fma_mix_f32 v130, v9, v23, v130 op_sel:[0,1,0] op_sel_hi:[0,1,0]
	v_add_f32_dpp v12, v12, v12 row_ror:2 row_mask:0xf bank_mask:0xf bound_ctrl:1
	v_pk_fma_f32 v[48:49], v[44:45], v[66:67], v[6:7] op_sel:[0,1,0]
	v_pk_fma_f32 v[50:51], v[46:47], v[66:67], v[8:9] op_sel:[0,1,0]
	v_add_f32_dpp v12, v12, v12 row_ror:4 row_mask:0xf bank_mask:0xf bound_ctrl:1
	v_add_f32_dpp v61, v61, v61 row_ror:4 row_mask:0xf bank_mask:0xa
	v_add_f32_dpp v61, v102, v102 row_ror:12 row_mask:0xf bank_mask:0x5
	v_add_f32_dpp v12, v12, v12 row_ror:8 row_mask:0xf bank_mask:0xf bound_ctrl:1
	v_pk_fma_f32 v[6:7], v[40:41], v[12:13], v[48:49] op_sel_hi:[1,0,1] neg_lo:[1,0,0] neg_hi:[1,0,0]
	v_pk_fma_f32 v[8:9], v[42:43], v[12:13], v[50:51] op_sel_hi:[1,0,1] neg_lo:[1,0,0] neg_hi:[1,0,0]
	ds_read_b128 v[20:23], v10 offset:61696
	ds_read_b128 v[28:31], v10 offset:62208
	ds_read_b128 v[24:27], v10 offset:61952
	s_waitcnt lgkmcnt(4)
	s_nop 0
	v_fma_mix_f32 v12, v6, v88, v180 op_sel_hi:[0,1,0]
	v_fma_mix_f32 v12, v7, v88, v12 op_sel:[0,1,0] op_sel_hi:[0,1,0]
	v_fma_mix_f32 v12, v8, v89, v12 op_sel_hi:[0,1,0]
	v_fma_mix_f32 v12, v9, v89, v12 op_sel:[0,1,0] op_sel_hi:[0,1,0]
	v_fma_mix_f32 v131, v6, v38, v180 op_sel_hi:[0,1,0]
	v_fma_mix_f32 v131, v7, v38, v131 op_sel:[0,1,0] op_sel_hi:[0,1,0]
	v_add_f32_dpp v12, v12, v12 row_ror:1 row_mask:0xf bank_mask:0xf bound_ctrl:1
	v_fma_mix_f32 v131, v8, v39, v131 op_sel_hi:[0,1,0]
	v_fma_mix_f32 v131, v9, v39, v131 op_sel:[0,1,0] op_sel_hi:[0,1,0]
	v_add_f32_dpp v12, v12, v12 row_ror:2 row_mask:0xf bank_mask:0xf bound_ctrl:1
	v_pk_fma_f32 v[48:49], v[96:97], v[68:69], v[6:7] op_sel_hi:[1,0,1]
	v_pk_fma_f32 v[50:51], v[98:99], v[68:69], v[8:9] op_sel_hi:[1,0,1]
	v_add_f32_dpp v12, v12, v12 row_ror:4 row_mask:0xf bank_mask:0xf bound_ctrl:1
	v_cndmask_b32_e64 v62, v105, v103, s[38:39]
	v_cndmask_b32_e64 v63, v103, v105, s[38:39]
	v_add_f32_dpp v12, v12, v12 row_ror:8 row_mask:0xf bank_mask:0xf bound_ctrl:1
	v_pk_fma_f32 v[6:7], v[92:93], v[12:13], v[48:49] op_sel_hi:[1,0,1] neg_lo:[1,0,0] neg_hi:[1,0,0]
	v_pk_fma_f32 v[8:9], v[94:95], v[12:13], v[50:51] op_sel_hi:[1,0,1] neg_lo:[1,0,0] neg_hi:[1,0,0]
	ds_read_b128 v[36:39], v10 offset:62720
	ds_read_b128 v[44:47], v10 offset:63232
	ds_read_b128 v[40:43], v10 offset:62976
	v_fma_mix_f32 v12, v6, v110, v180 op_sel_hi:[0,1,0]
	v_fma_mix_f32 v12, v7, v110, v12 op_sel:[0,1,0] op_sel_hi:[0,1,0]
	v_fma_mix_f32 v12, v8, v111, v12 op_sel_hi:[0,1,0]
	v_fma_mix_f32 v12, v9, v111, v12 op_sel:[0,1,0] op_sel_hi:[0,1,0]
	v_fma_mix_f32 v132, v6, v90, v180 op_sel_hi:[0,1,0]
	v_fma_mix_f32 v132, v7, v90, v132 op_sel:[0,1,0] op_sel_hi:[0,1,0]
	v_add_f32_dpp v12, v12, v12 row_ror:1 row_mask:0xf bank_mask:0xf bound_ctrl:1
	v_fma_mix_f32 v132, v8, v91, v132 op_sel_hi:[0,1,0]
	v_fma_mix_f32 v132, v9, v91, v132 op_sel:[0,1,0] op_sel_hi:[0,1,0]
	v_add_f32_dpp v12, v12, v12 row_ror:2 row_mask:0xf bank_mask:0xf bound_ctrl:1
	v_pk_fma_f32 v[48:49], v[118:119], v[68:69], v[6:7] op_sel:[0,1,0]
	v_pk_fma_f32 v[50:51], v[120:121], v[68:69], v[8:9] op_sel:[0,1,0]
	v_add_f32_dpp v12, v12, v12 row_ror:4 row_mask:0xf bank_mask:0xf bound_ctrl:1
	v_cndmask_b32_e64 v64, v61, v104, s[38:39]
	v_cndmask_b32_e64 v65, v104, v61, s[38:39]
	v_add_f32_dpp v12, v12, v12 row_ror:8 row_mask:0xf bank_mask:0xf bound_ctrl:1
	v_pk_fma_f32 v[6:7], v[114:115], v[12:13], v[48:49] op_sel_hi:[1,0,1] neg_lo:[1,0,0] neg_hi:[1,0,0]
	v_pk_fma_f32 v[8:9], v[116:117], v[12:13], v[50:51] op_sel_hi:[1,0,1] neg_lo:[1,0,0] neg_hi:[1,0,0]
	v_pk_mul_f32 v[6:7], v[6:7], v[106:107]
	v_pk_mul_f32 v[8:9], v[8:9], v[108:109]
	ds_read_b128 v[88:91], v10 offset:63744
	ds_read_b128 v[96:99], v10 offset:64256
	ds_read_b128 v[92:95], v10 offset:64000
	s_waitcnt lgkmcnt(3)
	s_nop 0
	v_fma_mix_f32 v12, v6, v20, v180 op_sel_hi:[0,1,0]
	v_fma_mix_f32 v12, v7, v20, v12 op_sel:[0,1,0] op_sel_hi:[0,1,0]
	v_fma_mix_f32 v12, v8, v21, v12 op_sel_hi:[0,1,0]
	v_fma_mix_f32 v12, v9, v21, v12 op_sel:[0,1,0] op_sel_hi:[0,1,0]
	v_fma_mix_f32 v133, v6, v112, v180 op_sel_hi:[0,1,0]
	v_fma_mix_f32 v133, v7, v112, v133 op_sel:[0,1,0] op_sel_hi:[0,1,0]
	v_add_f32_dpp v12, v12, v12 row_ror:1 row_mask:0xf bank_mask:0xf bound_ctrl:1
	v_fma_mix_f32 v133, v8, v113, v133 op_sel_hi:[0,1,0]
	v_fma_mix_f32 v133, v9, v113, v133 op_sel:[0,1,0] op_sel_hi:[0,1,0]
	v_add_f32_dpp v12, v12, v12 row_ror:2 row_mask:0xf bank_mask:0xf bound_ctrl:1
	v_pk_fma_f32 v[48:49], v[28:29], v[70:71], v[6:7] op_sel_hi:[1,0,1]
	v_pk_fma_f32 v[50:51], v[30:31], v[70:71], v[8:9] op_sel_hi:[1,0,1]
	v_add_f32_dpp v12, v12, v12 row_ror:4 row_mask:0xf bank_mask:0xf bound_ctrl:1
	v_add_f32_dpp v62, v63, v62 quad_perm:[2,3,0,1] row_mask:0xf bank_mask:0xf bound_ctrl:1
	v_add_f32_dpp v63, v65, v64 quad_perm:[2,3,0,1] row_mask:0xf bank_mask:0xf bound_ctrl:1
	v_add_f32_dpp v12, v12, v12 row_ror:8 row_mask:0xf bank_mask:0xf bound_ctrl:1
	v_pk_fma_f32 v[6:7], v[24:25], v[12:13], v[48:49] op_sel_hi:[1,0,1] neg_lo:[1,0,0] neg_hi:[1,0,0]
	v_pk_fma_f32 v[8:9], v[26:27], v[12:13], v[50:51] op_sel_hi:[1,0,1] neg_lo:[1,0,0] neg_hi:[1,0,0]
	ds_read_b128 v[110:113], v10 offset:64768
	ds_read_b128 v[106:109], v10 offset:64512
	ds_read_b128 v[118:121], v10 offset:65280
	ds_read_b128 v[114:117], v10 offset:65024
	v_fma_mix_f32 v12, v6, v36, v180 op_sel_hi:[0,1,0]
	v_fma_mix_f32 v12, v7, v36, v12 op_sel:[0,1,0] op_sel_hi:[0,1,0]
	v_fma_mix_f32 v12, v8, v37, v12 op_sel_hi:[0,1,0]
	v_fma_mix_f32 v12, v9, v37, v12 op_sel:[0,1,0] op_sel_hi:[0,1,0]
	v_fma_mix_f32 v134, v6, v22, v180 op_sel_hi:[0,1,0]
	v_fma_mix_f32 v134, v7, v22, v134 op_sel:[0,1,0] op_sel_hi:[0,1,0]
	v_add_f32_dpp v12, v12, v12 row_ror:1 row_mask:0xf bank_mask:0xf bound_ctrl:1
	v_fma_mix_f32 v134, v8, v23, v134 op_sel_hi:[0,1,0]
	v_fma_mix_f32 v134, v9, v23, v134 op_sel:[0,1,0] op_sel_hi:[0,1,0]
	v_add_f32_dpp v12, v12, v12 row_ror:2 row_mask:0xf bank_mask:0xf bound_ctrl:1
	v_pk_fma_f32 v[48:49], v[44:45], v[70:71], v[6:7] op_sel:[0,1,0]
	v_pk_fma_f32 v[50:51], v[46:47], v[70:71], v[8:9] op_sel:[0,1,0]
	v_add_f32_dpp v12, v12, v12 row_ror:4 row_mask:0xf bank_mask:0xf bound_ctrl:1
	v_cndmask_b32_e64 v65, v63, v62, s[40:41]
	v_cndmask_b32_e64 v62, v62, v63, s[40:41]
	v_add_f32_dpp v12, v12, v12 row_ror:8 row_mask:0xf bank_mask:0xf bound_ctrl:1
	v_pk_fma_f32 v[6:7], v[40:41], v[12:13], v[48:49] op_sel_hi:[1,0,1] neg_lo:[1,0,0] neg_hi:[1,0,0]
	v_pk_fma_f32 v[8:9], v[42:43], v[12:13], v[50:51] op_sel_hi:[1,0,1] neg_lo:[1,0,0] neg_hi:[1,0,0]
	s_waitcnt lgkmcnt(0)
	s_nop 0
	v_fma_mix_f32 v12, v6, v88, v180 op_sel_hi:[0,1,0]
	v_fma_mix_f32 v12, v7, v88, v12 op_sel:[0,1,0] op_sel_hi:[0,1,0]
	v_fma_mix_f32 v12, v8, v89, v12 op_sel_hi:[0,1,0]
	v_fma_mix_f32 v12, v9, v89, v12 op_sel:[0,1,0] op_sel_hi:[0,1,0]
	v_fma_mix_f32 v135, v6, v38, v180 op_sel_hi:[0,1,0]
	v_fma_mix_f32 v135, v7, v38, v135 op_sel:[0,1,0] op_sel_hi:[0,1,0]
	v_add_f32_dpp v12, v12, v12 row_ror:1 row_mask:0xf bank_mask:0xf bound_ctrl:1
	v_fma_mix_f32 v135, v8, v39, v135 op_sel_hi:[0,1,0]
	v_fma_mix_f32 v135, v9, v39, v135 op_sel:[0,1,0] op_sel_hi:[0,1,0]
	v_add_f32_dpp v12, v12, v12 row_ror:2 row_mask:0xf bank_mask:0xf bound_ctrl:1
	v_pk_fma_f32 v[48:49], v[96:97], v[72:73], v[6:7] op_sel_hi:[1,0,1]
	v_pk_fma_f32 v[50:51], v[98:99], v[72:73], v[8:9] op_sel_hi:[1,0,1]
	v_add_f32_dpp v12, v12, v12 row_ror:4 row_mask:0xf bank_mask:0xf bound_ctrl:1
	v_add_f32_dpp v62, v62, v65 quad_perm:[1,0,3,2] row_mask:0xf bank_mask:0xf bound_ctrl:1
	v_cvt_pk_bf16_f32 v62, v62, v62
	v_add_f32_dpp v12, v12, v12 row_ror:8 row_mask:0xf bank_mask:0xf bound_ctrl:1
	v_pk_fma_f32 v[6:7], v[92:93], v[12:13], v[48:49] op_sel_hi:[1,0,1] neg_lo:[1,0,0] neg_hi:[1,0,0]
	v_pk_fma_f32 v[8:9], v[94:95], v[12:13], v[50:51] op_sel_hi:[1,0,1] neg_lo:[1,0,0] neg_hi:[1,0,0]
	s_waitcnt lgkmcnt(0)
	s_barrier
	v_xor_b32_e32 v10, 0x10000, v10
	v_xor_b32_e32 v11, 0x1000, v11
	ds_read_b128 v[66:69], v11 offset:0
	ds_read_b128 v[20:23], v10 offset:256
	ds_read_b128 v[28:31], v10 offset:768
	ds_read_b128 v[24:27], v10 offset:512
	ds_read_b128 v[36:39], v10 offset:1280
	ds_read_b128 v[44:47], v10 offset:1792
	ds_read_b128 v[40:43], v10 offset:1536
	v_fma_mix_f32 v12, v6, v110, v180 op_sel_hi:[0,1,0]
	v_fma_mix_f32 v12, v7, v110, v12 op_sel:[0,1,0] op_sel_hi:[0,1,0]
	v_fma_mix_f32 v12, v8, v111, v12 op_sel_hi:[0,1,0]
	v_fma_mix_f32 v12, v9, v111, v12 op_sel:[0,1,0] op_sel_hi:[0,1,0]
	v_fma_mix_f32 v136, v6, v90, v180 op_sel_hi:[0,1,0]
	v_fma_mix_f32 v136, v7, v90, v136 op_sel:[0,1,0] op_sel_hi:[0,1,0]
	v_add_f32_dpp v12, v12, v12 row_ror:1 row_mask:0xf bank_mask:0xf bound_ctrl:1
	v_fma_mix_f32 v136, v8, v91, v136 op_sel_hi:[0,1,0]
	v_fma_mix_f32 v136, v9, v91, v136 op_sel:[0,1,0] op_sel_hi:[0,1,0]
	v_add_f32_dpp v12, v12, v12 row_ror:2 row_mask:0xf bank_mask:0xf bound_ctrl:1
	v_pk_fma_f32 v[48:49], v[118:119], v[72:73], v[6:7] op_sel:[0,1,0]
	v_pk_fma_f32 v[50:51], v[120:121], v[72:73], v[8:9] op_sel:[0,1,0]
	v_add_f32_dpp v12, v12, v12 row_ror:4 row_mask:0xf bank_mask:0xf bound_ctrl:1
	global_store_short v[2:3], v62, off
	v_lshl_add_u64 v[2:3], v[2:3], 0, s[84:85]
	v_add_f32_dpp v12, v12, v12 row_ror:8 row_mask:0xf bank_mask:0xf bound_ctrl:1
	v_pk_fma_f32 v[6:7], v[114:115], v[12:13], v[48:49] op_sel_hi:[1,0,1] neg_lo:[1,0,0] neg_hi:[1,0,0]
	v_pk_fma_f32 v[8:9], v[116:117], v[12:13], v[50:51] op_sel_hi:[1,0,1] neg_lo:[1,0,0] neg_hi:[1,0,0]
	v_pk_mul_f32 v[6:7], v[6:7], v[106:107]
	v_pk_mul_f32 v[8:9], v[8:9], v[108:109]
	v_fma_mix_f32 v137, v6, v112, v180 op_sel_hi:[0,1,0]
	v_fma_mix_f32 v137, v7, v112, v137 op_sel:[0,1,0] op_sel_hi:[0,1,0]
	v_fma_mix_f32 v137, v8, v113, v137 op_sel_hi:[0,1,0]
	v_fma_mix_f32 v137, v9, v113, v137 op_sel:[0,1,0] op_sel_hi:[0,1,0]
	v_mov_b32_e64 v170, v2
	v_mov_b32_e64 v171, v3
	s_mov_b64 s[100:101], -1
	s_nop 0
	s_cmp_lg_u32 s28, 0x800000
	s_cbranch_scc1 .Lscan_cons_chunk
	v_add_f32_dpp v130, v130, v130 row_ror:8 row_mask:0xf bank_mask:0xc
	v_add_f32_dpp v130, v122, v122 row_ror:8 row_mask:0xf bank_mask:0x3
	v_add_f32_dpp v131, v131, v131 row_ror:8 row_mask:0xf bank_mask:0xc
	v_add_f32_dpp v131, v123, v123 row_ror:8 row_mask:0xf bank_mask:0x3
	v_add_f32_dpp v132, v132, v132 row_ror:8 row_mask:0xf bank_mask:0xc
	v_add_f32_dpp v132, v124, v124 row_ror:8 row_mask:0xf bank_mask:0x3
	v_add_f32_dpp v133, v133, v133 row_ror:8 row_mask:0xf bank_mask:0xc
	v_add_f32_dpp v133, v125, v125 row_ror:8 row_mask:0xf bank_mask:0x3
	v_add_f32_dpp v134, v134, v134 row_ror:8 row_mask:0xf bank_mask:0xc
	v_add_f32_dpp v134, v126, v126 row_ror:8 row_mask:0xf bank_mask:0x3
	v_add_f32_dpp v135, v135, v135 row_ror:8 row_mask:0xf bank_mask:0xc
	v_add_f32_dpp v135, v127, v127 row_ror:8 row_mask:0xf bank_mask:0x3
	v_add_f32_dpp v136, v136, v136 row_ror:8 row_mask:0xf bank_mask:0xc
	v_add_f32_dpp v136, v128, v128 row_ror:8 row_mask:0xf bank_mask:0x3
	v_add_f32_dpp v137, v137, v137 row_ror:8 row_mask:0xf bank_mask:0xc
	v_add_f32_dpp v137, v129, v129 row_ror:8 row_mask:0xf bank_mask:0x3
	v_add_f32_dpp v134, v134, v134 row_ror:4 row_mask:0xf bank_mask:0xa
	v_add_f32_dpp v134, v130, v130 row_ror:12 row_mask:0xf bank_mask:0x5
	v_add_f32_dpp v135, v135, v135 row_ror:4 row_mask:0xf bank_mask:0xa
	v_add_f32_dpp v135, v131, v131 row_ror:12 row_mask:0xf bank_mask:0x5
	v_add_f32_dpp v136, v136, v136 row_ror:4 row_mask:0xf bank_mask:0xa
	v_add_f32_dpp v136, v132, v132 row_ror:12 row_mask:0xf bank_mask:0x5
	v_add_f32_dpp v137, v137, v137 row_ror:4 row_mask:0xf bank_mask:0xa
	v_add_f32_dpp v137, v133, v133 row_ror:12 row_mask:0xf bank_mask:0x5
	v_cndmask_b32_e64 v62, v136, v134, s[38:39]
	v_cndmask_b32_e64 v63, v134, v136, s[38:39]
	v_cndmask_b32_e64 v64, v137, v135, s[38:39]
	v_cndmask_b32_e64 v65, v135, v137, s[38:39]
	v_add_f32_dpp v62, v63, v62 quad_perm:[2,3,0,1] row_mask:0xf bank_mask:0xf bound_ctrl:1
	s_nop 0
	v_add_f32_dpp v63, v65, v64 quad_perm:[2,3,0,1] row_mask:0xf bank_mask:0xf bound_ctrl:1
	v_cndmask_b32_e64 v65, v63, v62, s[40:41]
	v_cndmask_b32_e64 v62, v62, v63, s[40:41]
	s_nop 1
	v_add_f32_dpp v62, v62, v65 quad_perm:[1,0,3,2] row_mask:0xf bank_mask:0xf bound_ctrl:1
	v_cvt_pk_bf16_f32 v62, v62, v62
	global_store_short v[2:3], v62, off
	s_branch .LBB0_53
